# xattn PV loop and PEER top-k stage-1 loop: 16 fragment loads in flight instead of 2 (hand-written loops, same MFMA order)
# speedup vs baseline: 1.1715x; 1.0248x over previous
; #define MFMA(a, b, c) __builtin_amdgcn_mfma_f32_32x32x16_bf16((a), (b), (c), 0, 0, 0)
; DI f32x16 zero16() { f32x16 z; for (int i = 0; i < 16; ++i) z[i] = 0.f; return z; }
; DI void phase_xattn(const Params& p) {
;     ...
;     f32x16 Sx[8];
; #pragma unroll
;     for (int kt = 0; kt < 8; ++kt) Sx[kt] = zero16();
;     const u16* qrow = qx + (((size_t)(b * 128 + qt) * 4 + h) * 16) * 512 + lane * 8;
;     const u16* krow = mk + (((size_t)(b * 4 + h) * 8) * 16) * 512 + lane * 8;
; #pragma unroll 2
;     for (int ks = 0; ks < 16; ++ks) {
;       bf16x8 qf = ldg8(qrow + ks * 512);
; #pragma unroll
;       for (int kt = 0; kt < 8; ++kt) Sx[kt] = MFMA(ldg8(krow + (kt * 16 + ks) * 512), qf, Sx[kt]);
;     }
;     float mx = -INFINITY;
; #pragma unroll
;     for (int kt = 0; kt < 8; ++kt)
; #pragma unroll
;       for (int i = 0; i < 16; ++i) mx = fmaxf(mx, Sx[kt][i]);
;     mx = fmaxf(mx, __shfl_xor(mx, 32));
.LBB0_735:
	v_lshl_add_u64 v[156:157], v[136:137], 0, s[18:19]
	v_add_co_u32_e32 v160, vcc, s20, v156
	v_lshl_add_u64 v[158:159], v[138:139], 0, s[18:19]
	s_nop 0
	v_addc_co_u32_e32 v161, vcc, 0, v157, vcc
	v_add_co_u32_e32 v172, vcc, s21, v158
	s_add_u32 s18, s18, 0x800
	s_nop 0
	v_addc_co_u32_e32 v173, vcc, 0, v159, vcc
	v_add_co_u32_e32 v228, vcc, s22, v158
	s_addc_u32 s19, s19, 0
	s_nop 0
	v_addc_co_u32_e32 v229, vcc, 0, v159, vcc
	v_add_co_u32_e32 v230, vcc, s23, v158
	s_cmpk_lg_i32 s18, 0x4000
	s_nop 0
	v_addc_co_u32_e32 v231, vcc, 0, v159, vcc
	v_add_co_u32_e32 v232, vcc, s24, v158
	s_nop 1
	v_addc_co_u32_e32 v233, vcc, 0, v159, vcc
	v_add_co_u32_e32 v234, vcc, s25, v158
	s_nop 1
	v_addc_co_u32_e32 v235, vcc, 0, v159, vcc
	v_add_co_u32_e32 v236, vcc, s26, v158
	s_nop 1
	v_addc_co_u32_e32 v237, vcc, 0, v159, vcc
	v_add_co_u32_e32 v238, vcc, s27, v158
	s_nop 1
	v_addc_co_u32_e32 v239, vcc, 0, v159, vcc
	v_add_co_u32_e32 v240, vcc, s28, v158
	s_nop 1
	v_addc_co_u32_e32 v241, vcc, 0, v159, vcc
	global_load_dwordx4 v[156:159], v[172:173], off
	global_load_dwordx4 v[180:183], v[160:161], off
	global_load_dwordx4 v[184:187], v[228:229], off
	global_load_dwordx4 v[188:191], v[230:231], off
	global_load_dwordx4 v[192:195], v[232:233], off
	global_load_dwordx4 v[196:199], v[234:235], off
	global_load_dwordx4 v[200:203], v[236:237], off
	global_load_dwordx4 v[212:215], v[238:239], off
	global_load_dwordx4 v[216:219], v[240:241], off
	global_load_dwordx4 v[220:223], v[172:173], off offset:1024
	global_load_dwordx4 v[224:227], v[160:161], off offset:1024
	s_waitcnt vmcnt(9)
	v_mfma_f32_32x32x16_bf16 v[112:127], v[156:159], v[180:183], v[112:127]
	global_load_dwordx4 v[156:159], v[228:229], off offset:1024
	s_waitcnt vmcnt(9)
	v_mfma_f32_32x32x16_bf16 v[96:111], v[184:187], v[180:183], v[96:111]
	global_load_dwordx4 v[184:187], v[230:231], off offset:1024
	s_waitcnt vmcnt(9)
	v_mfma_f32_32x32x16_bf16 v[80:95], v[188:191], v[180:183], v[80:95]
	global_load_dwordx4 v[188:191], v[232:233], off offset:1024
	s_waitcnt vmcnt(9)
	v_mfma_f32_32x32x16_bf16 v[64:79], v[192:195], v[180:183], v[64:79]
	global_load_dwordx4 v[192:195], v[234:235], off offset:1024
	s_waitcnt vmcnt(9)
	v_mfma_f32_32x32x16_bf16 v[48:63], v[196:199], v[180:183], v[48:63]
	global_load_dwordx4 v[196:199], v[236:237], off offset:1024
	s_waitcnt vmcnt(9)
	v_mfma_f32_32x32x16_bf16 v[32:47], v[200:203], v[180:183], v[32:47]
	global_load_dwordx4 v[200:203], v[238:239], off offset:1024
	s_waitcnt vmcnt(9)
	v_mfma_f32_32x32x16_bf16 v[16:31], v[212:215], v[180:183], v[16:31]
	global_load_dwordx4 v[212:215], v[240:241], off offset:1024
	s_waitcnt vmcnt(9)
	v_mfma_f32_32x32x16_bf16 v[0:15], v[216:219], v[180:183], v[0:15]
	s_waitcnt vmcnt(7)
	v_mfma_f32_32x32x16_bf16 v[112:127], v[220:223], v[224:227], v[112:127]
	s_waitcnt vmcnt(6)
	v_mfma_f32_32x32x16_bf16 v[96:111], v[156:159], v[224:227], v[96:111]
	s_waitcnt vmcnt(5)
	v_mfma_f32_32x32x16_bf16 v[80:95], v[184:187], v[224:227], v[80:95]
	s_waitcnt vmcnt(4)
	v_mfma_f32_32x32x16_bf16 v[64:79], v[188:191], v[224:227], v[64:79]
	s_waitcnt vmcnt(3)
	v_mfma_f32_32x32x16_bf16 v[48:63], v[192:195], v[224:227], v[48:63]
	s_waitcnt vmcnt(2)
	v_mfma_f32_32x32x16_bf16 v[32:47], v[196:199], v[224:227], v[32:47]
	s_waitcnt vmcnt(1)
	v_mfma_f32_32x32x16_bf16 v[16:31], v[200:203], v[224:227], v[16:31]
	s_waitcnt vmcnt(0)
	v_mfma_f32_32x32x16_bf16 v[0:15], v[212:215], v[224:227], v[0:15]
	s_cbranch_scc1 .LBB0_735
	v_max3_f32 v136, v112, s29, v113
	v_max3_f32 v136, v136, v114, v115
	v_max3_f32 v136, v136, v116, v117
	v_max3_f32 v136, v136, v118, v119
	v_max3_f32 v136, v136, v120, v121
	v_max3_f32 v136, v136, v122, v123
	v_max3_f32 v136, v136, v124, v125
	v_max3_f32 v136, v136, v126, v127
	v_max3_f32 v136, v136, v96, v97
	v_max3_f32 v136, v136, v98, v99
	v_max3_f32 v136, v136, v100, v101
	v_max3_f32 v136, v136, v102, v103
	v_max3_f32 v136, v136, v104, v105
	v_max3_f32 v136, v136, v106, v107
	v_max3_f32 v136, v136, v108, v109
	v_max3_f32 v136, v136, v110, v111
	v_max3_f32 v136, v136, v80, v81
	v_max3_f32 v136, v136, v82, v83
	v_max3_f32 v136, v136, v84, v85
	v_max3_f32 v136, v136, v86, v87
	v_max3_f32 v136, v136, v88, v89
	v_max3_f32 v136, v136, v90, v91
	v_max3_f32 v136, v136, v92, v93
	v_max3_f32 v136, v136, v94, v95
	v_max3_f32 v136, v136, v64, v65
	v_max3_f32 v136, v136, v66, v67
	v_max3_f32 v136, v136, v68, v69
	v_max3_f32 v136, v136, v70, v71
	v_max3_f32 v136, v136, v72, v73
	v_max3_f32 v136, v136, v74, v75
	v_max3_f32 v136, v136, v76, v77
	v_max3_f32 v136, v136, v78, v79
	v_max3_f32 v136, v136, v48, v49
	v_max3_f32 v136, v136, v50, v51
	v_max3_f32 v136, v136, v52, v53
	v_max3_f32 v136, v136, v54, v55
	v_max3_f32 v136, v136, v56, v57
	v_max3_f32 v136, v136, v58, v59
	v_max3_f32 v136, v136, v60, v61
	v_max3_f32 v136, v136, v62, v63
	v_max3_f32 v136, v136, v32, v33
	v_max3_f32 v136, v136, v34, v35
	v_max3_f32 v136, v136, v36, v37
	v_max3_f32 v136, v136, v38, v39
	v_max3_f32 v136, v136, v40, v41
	v_max3_f32 v136, v136, v42, v43
	v_max3_f32 v136, v136, v44, v45
	v_max3_f32 v136, v136, v46, v47
	v_max3_f32 v136, v136, v16, v17
	v_max3_f32 v136, v136, v18, v19
	v_max3_f32 v136, v136, v20, v21
	v_max3_f32 v136, v136, v22, v23
	v_max3_f32 v136, v136, v24, v25
	v_max3_f32 v136, v136, v26, v27
	v_max3_f32 v136, v136, v28, v29
	v_max3_f32 v136, v136, v30, v31
	v_max3_f32 v136, v136, v0, v1
	v_max3_f32 v136, v136, v2, v3
	v_max3_f32 v136, v136, v4, v5
	v_max3_f32 v136, v136, v6, v7
	v_max3_f32 v136, v136, v8, v9
	v_max3_f32 v136, v136, v10, v11
	v_max3_f32 v136, v136, v12, v13
	v_max3_f32 v137, v136, v14, v15
	ds_bpermute_b32 v138, v151, v137
	v_add_u32_e32 v136, v152, v155
	v_lshlrev_b32_e32 v128, 9, v128
	s_waitcnt lgkmcnt(0)
; DI void phase_xattn(const Params& p) {
;     ...
;     float ls = 0.f;
;     bf16x8 Pf[8][2];
; #pragma unroll
;     for (int kt = 0; kt < 8; ++kt) {
;       float pv[16];
; #pragma unroll
;       for (int i = 0; i < 16; ++i) { pv[i] = __expf((Sx[kt][i] - mx) * 0.0625f); ls += pv[i]; }
; #pragma unroll
;       for (int s = 0; s < 2; ++s) Pf[kt][s] = pack8(pv[8 * s], pv[8 * s + 1], pv[8 * s + 2], pv[8 * s + 3], pv[8 * s + 4], pv[8 * s + 5], pv[8 * s + 6], pv[8 * s + 7]);
;     }
	v_max_f32_e32 v138, v138, v138
	v_max_f32_e32 v137, v137, v138
	v_sub_f32_e32 v112, v112, v137
	v_sub_f32_e32 v113, v113, v137
	v_mul_f32_e32 v112, 0x3d800000, v112
	v_mul_f32_e32 v113, 0x3d800000, v113
	v_mul_f32_e32 v112, 0x3fb8aa3b, v112
	v_exp_f32_e32 v138, v112
	v_mul_f32_e32 v112, 0x3fb8aa3b, v113
	v_exp_f32_e32 v139, v112
	v_sub_f32_e32 v112, v114, v137
	v_mul_f32_e32 v112, 0x3d800000, v112
	v_mul_f32_e32 v112, 0x3fb8aa3b, v112
	v_exp_f32_e32 v155, v112
	v_sub_f32_e32 v112, v115, v137
	v_mul_f32_e32 v112, 0x3d800000, v112
	v_mul_f32_e32 v112, 0x3fb8aa3b, v112
	v_exp_f32_e32 v156, v112
	v_sub_f32_e32 v112, v116, v137
	v_mul_f32_e32 v112, 0x3d800000, v112
	v_mul_f32_e32 v112, 0x3fb8aa3b, v112
	v_exp_f32_e32 v157, v112
	v_sub_f32_e32 v112, v117, v137
	v_mul_f32_e32 v112, 0x3d800000, v112
	v_mul_f32_e32 v112, 0x3fb8aa3b, v112
	v_exp_f32_e32 v158, v112
	v_sub_f32_e32 v112, v118, v137
	v_mul_f32_e32 v112, 0x3d800000, v112
	v_mul_f32_e32 v112, 0x3fb8aa3b, v112
	v_exp_f32_e32 v159, v112
	v_sub_f32_e32 v112, v119, v137
	v_mul_f32_e32 v112, 0x3d800000, v112
	v_mul_f32_e32 v112, 0x3fb8aa3b, v112
	v_exp_f32_e32 v160, v112
	v_sub_f32_e32 v112, v120, v137
	v_mul_f32_e32 v112, 0x3d800000, v112
	v_mul_f32_e32 v112, 0x3fb8aa3b, v112
	v_exp_f32_e32 v120, v112
	v_sub_f32_e32 v112, v121, v137
	v_mul_f32_e32 v112, 0x3d800000, v112
	v_mul_f32_e32 v112, 0x3fb8aa3b, v112
	v_exp_f32_e32 v121, v112
	v_sub_f32_e32 v112, v122, v137
	v_mul_f32_e32 v112, 0x3d800000, v112
	v_mul_f32_e32 v112, 0x3fb8aa3b, v112
	v_exp_f32_e32 v122, v112
	v_sub_f32_e32 v112, v123, v137
	v_mul_f32_e32 v112, 0x3d800000, v112
	v_mul_f32_e32 v112, 0x3fb8aa3b, v112
	v_exp_f32_e32 v123, v112
	v_sub_f32_e32 v112, v124, v137
	v_mul_f32_e32 v112, 0x3d800000, v112
	v_mul_f32_e32 v112, 0x3fb8aa3b, v112
	v_exp_f32_e32 v124, v112
	v_sub_f32_e32 v112, v125, v137
	v_mul_f32_e32 v112, 0x3d800000, v112
	v_mul_f32_e32 v112, 0x3fb8aa3b, v112
	v_exp_f32_e32 v125, v112
	v_sub_f32_e32 v112, v126, v137
	v_mul_f32_e32 v112, 0x3d800000, v112
	v_mul_f32_e32 v112, 0x3fb8aa3b, v112
	v_exp_f32_e32 v126, v112
	v_sub_f32_e32 v112, v127, v137
	v_mul_f32_e32 v112, 0x3d800000, v112
	v_mul_f32_e32 v112, 0x3fb8aa3b, v112
	v_exp_f32_e32 v127, v112
	v_cvt_pk_bf16_f32 v112, v138, v139
	v_add_f32_e32 v138, 0, v138
	v_add_f32_e32 v138, v139, v138
	v_add_f32_e32 v138, v155, v138
	v_add_f32_e32 v138, v156, v138
	v_add_f32_e32 v138, v157, v138
	v_add_f32_e32 v138, v158, v138
	v_add_f32_e32 v138, v159, v138
	v_sub_f32_e32 v96, v96, v137
	v_add_f32_e32 v138, v160, v138
	v_mul_f32_e32 v96, 0x3d800000, v96
	v_cvt_pk_bf16_f32 v116, v120, v121
	v_add_f32_e32 v120, v120, v138
	v_mul_f32_e32 v96, 0x3fb8aa3b, v96
	v_add_f32_e32 v120, v121, v120
	v_exp_f32_e32 v121, v96
	v_sub_f32_e32 v96, v97, v137
	v_mul_f32_e32 v96, 0x3d800000, v96
	v_mul_f32_e32 v96, 0x3fb8aa3b, v96
	v_cvt_pk_bf16_f32 v117, v122, v123
	v_add_f32_e32 v120, v122, v120
	v_exp_f32_e32 v122, v96
	v_sub_f32_e32 v96, v98, v137
	v_mul_f32_e32 v96, 0x3d800000, v96
	v_mul_f32_e32 v96, 0x3fb8aa3b, v96
	v_add_f32_e32 v120, v123, v120
	v_exp_f32_e32 v123, v96
	v_sub_f32_e32 v96, v99, v137
	v_mul_f32_e32 v96, 0x3d800000, v96
	v_mul_f32_e32 v96, 0x3fb8aa3b, v96
	v_cvt_pk_bf16_f32 v118, v124, v125
	v_add_f32_e32 v120, v124, v120
	v_exp_f32_e32 v124, v96
	v_sub_f32_e32 v96, v100, v137
	v_mul_f32_e32 v96, 0x3d800000, v96
	v_mul_f32_e32 v96, 0x3fb8aa3b, v96
	v_add_f32_e32 v120, v125, v120
	v_exp_f32_e32 v125, v96
	v_sub_f32_e32 v96, v101, v137
	v_mul_f32_e32 v96, 0x3d800000, v96
	v_mul_f32_e32 v96, 0x3fb8aa3b, v96
	v_cvt_pk_bf16_f32 v119, v126, v127
	v_add_f32_e32 v120, v126, v120
	v_exp_f32_e32 v126, v96
	v_sub_f32_e32 v96, v102, v137
	v_mul_f32_e32 v96, 0x3d800000, v96
	v_mul_f32_e32 v96, 0x3fb8aa3b, v96
	v_add_f32_e32 v120, v127, v120
	v_exp_f32_e32 v127, v96
	v_sub_f32_e32 v96, v103, v137
	v_mul_f32_e32 v96, 0x3d800000, v96
	v_mul_f32_e32 v96, 0x3fb8aa3b, v96
	v_exp_f32_e32 v138, v96
	v_sub_f32_e32 v96, v104, v137
	v_mul_f32_e32 v96, 0x3d800000, v96
	v_mul_f32_e32 v96, 0x3fb8aa3b, v96
	v_exp_f32_e32 v104, v96
	v_sub_f32_e32 v96, v105, v137
	v_mul_f32_e32 v96, 0x3d800000, v96
	v_add_f32_e32 v120, v121, v120
	v_mul_f32_e32 v96, 0x3fb8aa3b, v96
	v_add_f32_e32 v120, v122, v120
	v_exp_f32_e32 v105, v96
	v_sub_f32_e32 v96, v106, v137
	v_add_f32_e32 v120, v123, v120
	v_mul_f32_e32 v96, 0x3d800000, v96
	v_add_f32_e32 v120, v124, v120
	v_mul_f32_e32 v96, 0x3fb8aa3b, v96
	v_add_f32_e32 v120, v125, v120
	v_exp_f32_e32 v106, v96
	v_sub_f32_e32 v96, v107, v137
	v_add_f32_e32 v120, v126, v120
	v_mul_f32_e32 v96, 0x3d800000, v96
	v_add_f32_e32 v120, v127, v120
	v_sub_f32_e32 v80, v80, v137
	v_mul_f32_e32 v96, 0x3fb8aa3b, v96
	v_add_f32_e32 v120, v138, v120
	v_mul_f32_e32 v80, 0x3d800000, v80
	v_exp_f32_e32 v107, v96
	v_sub_f32_e32 v96, v108, v137
	v_cvt_pk_bf16_f32 v100, v104, v105
	v_add_f32_e32 v104, v104, v120
	v_mul_f32_e32 v80, 0x3fb8aa3b, v80
	v_mul_f32_e32 v96, 0x3d800000, v96
	v_add_f32_e32 v104, v105, v104
	v_exp_f32_e32 v105, v80
	v_sub_f32_e32 v80, v81, v137
	v_mul_f32_e32 v96, 0x3fb8aa3b, v96
	v_mul_f32_e32 v80, 0x3d800000, v80
	v_exp_f32_e32 v108, v96
	v_sub_f32_e32 v96, v109, v137
	v_mul_f32_e32 v80, 0x3fb8aa3b, v80
	v_mul_f32_e32 v96, 0x3d800000, v96
	v_cvt_pk_bf16_f32 v101, v106, v107
	v_add_f32_e32 v104, v106, v104
	v_exp_f32_e32 v106, v80
	v_sub_f32_e32 v80, v82, v137
	v_mul_f32_e32 v96, 0x3fb8aa3b, v96
	v_mul_f32_e32 v80, 0x3d800000, v80
	v_exp_f32_e32 v109, v96
	v_sub_f32_e32 v96, v110, v137
	v_mul_f32_e32 v80, 0x3fb8aa3b, v80
	v_mul_f32_e32 v96, 0x3d800000, v96
	v_add_f32_e32 v104, v107, v104
	v_exp_f32_e32 v107, v80
	v_sub_f32_e32 v80, v83, v137
	v_mul_f32_e32 v96, 0x3fb8aa3b, v96
; DI void phase_xattn(const Params& p) {
;     ...
; #pragma unroll
;     for (int kt = 0; kt < 8; ++kt) {
;       float pv[16];
; #pragma unroll
;       for (int i = 0; i < 16; ++i) { pv[i] = __expf((Sx[kt][i] - mx) * 0.0625f); ls += pv[i]; }
; #pragma unroll
;       for (int s = 0; s < 2; ++s) Pf[kt][s] = pack8(pv[8 * s], pv[8 * s + 1], pv[8 * s + 2], pv[8 * s + 3], pv[8 * s + 4], pv[8 * s + 5], pv[8 * s + 6], pv[8 * s + 7]);
;     }
	v_mul_f32_e32 v80, 0x3d800000, v80
	v_exp_f32_e32 v110, v96
	v_sub_f32_e32 v96, v111, v137
	v_mul_f32_e32 v80, 0x3fb8aa3b, v80
	v_mul_f32_e32 v96, 0x3d800000, v96
	v_cvt_pk_bf16_f32 v102, v108, v109
	v_add_f32_e32 v104, v108, v104
	v_exp_f32_e32 v108, v80
	v_sub_f32_e32 v80, v84, v137
	v_mul_f32_e32 v96, 0x3fb8aa3b, v96
	v_mul_f32_e32 v80, 0x3d800000, v80
	v_exp_f32_e32 v111, v96
	v_mul_f32_e32 v80, 0x3fb8aa3b, v80
	v_add_f32_e32 v104, v109, v104
	v_exp_f32_e32 v109, v80
	v_sub_f32_e32 v80, v85, v137
	v_mul_f32_e32 v80, 0x3d800000, v80
	v_mul_f32_e32 v80, 0x3fb8aa3b, v80
	v_cvt_pk_bf16_f32 v103, v110, v111
	v_add_f32_e32 v104, v110, v104
	v_exp_f32_e32 v110, v80
	v_sub_f32_e32 v80, v86, v137
	v_mul_f32_e32 v80, 0x3d800000, v80
	v_mul_f32_e32 v80, 0x3fb8aa3b, v80
	v_add_f32_e32 v104, v111, v104
	v_exp_f32_e32 v111, v80
	v_sub_f32_e32 v80, v87, v137
	v_mul_f32_e32 v80, 0x3d800000, v80
	v_mul_f32_e32 v80, 0x3fb8aa3b, v80
	v_exp_f32_e32 v120, v80
	v_sub_f32_e32 v80, v88, v137
	v_mul_f32_e32 v80, 0x3d800000, v80
	v_mul_f32_e32 v80, 0x3fb8aa3b, v80
	v_exp_f32_e32 v88, v80
	v_sub_f32_e32 v80, v89, v137
	v_mul_f32_e32 v80, 0x3d800000, v80
	v_add_f32_e32 v104, v105, v104
	v_mul_f32_e32 v80, 0x3fb8aa3b, v80
	v_add_f32_e32 v104, v106, v104
	v_exp_f32_e32 v89, v80
	v_sub_f32_e32 v80, v90, v137
	v_add_f32_e32 v104, v107, v104
	v_mul_f32_e32 v80, 0x3d800000, v80
	v_add_f32_e32 v104, v108, v104
	v_mul_f32_e32 v80, 0x3fb8aa3b, v80
	v_add_f32_e32 v104, v109, v104
	v_exp_f32_e32 v90, v80
	v_sub_f32_e32 v80, v91, v137
	v_add_f32_e32 v104, v110, v104
	v_mul_f32_e32 v80, 0x3d800000, v80
	v_add_f32_e32 v104, v111, v104
	v_sub_f32_e32 v64, v64, v137
	v_mul_f32_e32 v80, 0x3fb8aa3b, v80
	v_add_f32_e32 v104, v120, v104
	v_mul_f32_e32 v64, 0x3d800000, v64
	v_exp_f32_e32 v91, v80
	v_sub_f32_e32 v80, v92, v137
	v_cvt_pk_bf16_f32 v84, v88, v89
	v_add_f32_e32 v88, v88, v104
	v_mul_f32_e32 v64, 0x3fb8aa3b, v64
	v_mul_f32_e32 v80, 0x3d800000, v80
	v_add_f32_e32 v88, v89, v88
	v_exp_f32_e32 v89, v64
	v_sub_f32_e32 v64, v65, v137
	v_mul_f32_e32 v80, 0x3fb8aa3b, v80
	v_mul_f32_e32 v64, 0x3d800000, v64
	v_exp_f32_e32 v92, v80
	v_sub_f32_e32 v80, v93, v137
	v_mul_f32_e32 v64, 0x3fb8aa3b, v64
	v_mul_f32_e32 v80, 0x3d800000, v80
	v_cvt_pk_bf16_f32 v85, v90, v91
	v_add_f32_e32 v88, v90, v88
	v_exp_f32_e32 v90, v64
	v_sub_f32_e32 v64, v66, v137
	v_mul_f32_e32 v80, 0x3fb8aa3b, v80
	v_mul_f32_e32 v64, 0x3d800000, v64
	v_exp_f32_e32 v93, v80
	v_sub_f32_e32 v80, v94, v137
	v_mul_f32_e32 v64, 0x3fb8aa3b, v64
	v_mul_f32_e32 v80, 0x3d800000, v80
	v_add_f32_e32 v88, v91, v88
	v_exp_f32_e32 v91, v64
	v_sub_f32_e32 v64, v67, v137
	v_mul_f32_e32 v80, 0x3fb8aa3b, v80
	v_mul_f32_e32 v64, 0x3d800000, v64
	v_exp_f32_e32 v94, v80
	v_sub_f32_e32 v80, v95, v137
	v_mul_f32_e32 v64, 0x3fb8aa3b, v64
	v_mul_f32_e32 v80, 0x3d800000, v80
	v_cvt_pk_bf16_f32 v86, v92, v93
	v_add_f32_e32 v88, v92, v88
	v_exp_f32_e32 v92, v64
	v_sub_f32_e32 v64, v68, v137
	v_mul_f32_e32 v80, 0x3fb8aa3b, v80
	v_mul_f32_e32 v64, 0x3d800000, v64
	v_exp_f32_e32 v95, v80
	v_mul_f32_e32 v64, 0x3fb8aa3b, v64
	v_add_f32_e32 v88, v93, v88
	v_exp_f32_e32 v93, v64
	v_sub_f32_e32 v64, v69, v137
	v_mul_f32_e32 v64, 0x3d800000, v64
	v_mul_f32_e32 v64, 0x3fb8aa3b, v64
	v_cvt_pk_bf16_f32 v87, v94, v95
	v_add_f32_e32 v88, v94, v88
	v_exp_f32_e32 v94, v64
	v_sub_f32_e32 v64, v70, v137
	v_mul_f32_e32 v64, 0x3d800000, v64
	v_mul_f32_e32 v64, 0x3fb8aa3b, v64
	v_add_f32_e32 v88, v95, v88
	v_exp_f32_e32 v95, v64
	v_sub_f32_e32 v64, v71, v137
	v_mul_f32_e32 v64, 0x3d800000, v64
	v_mul_f32_e32 v64, 0x3fb8aa3b, v64
	v_exp_f32_e32 v104, v64
	v_sub_f32_e32 v64, v72, v137
	v_mul_f32_e32 v64, 0x3d800000, v64
	v_mul_f32_e32 v64, 0x3fb8aa3b, v64
	v_exp_f32_e32 v72, v64
	v_sub_f32_e32 v64, v73, v137
	v_mul_f32_e32 v64, 0x3d800000, v64
	v_add_f32_e32 v88, v89, v88
	v_mul_f32_e32 v64, 0x3fb8aa3b, v64
	v_add_f32_e32 v88, v90, v88
	v_exp_f32_e32 v73, v64
	v_sub_f32_e32 v64, v74, v137
	v_add_f32_e32 v88, v91, v88
	v_mul_f32_e32 v64, 0x3d800000, v64
	v_add_f32_e32 v88, v92, v88
	v_mul_f32_e32 v64, 0x3fb8aa3b, v64
	v_add_f32_e32 v88, v93, v88
	v_exp_f32_e32 v74, v64
	v_sub_f32_e32 v64, v75, v137
	v_add_f32_e32 v88, v94, v88
	v_mul_f32_e32 v64, 0x3d800000, v64
	v_add_f32_e32 v88, v95, v88
	v_sub_f32_e32 v48, v48, v137
	v_mul_f32_e32 v64, 0x3fb8aa3b, v64
	v_add_f32_e32 v88, v104, v88
	v_mul_f32_e32 v48, 0x3d800000, v48
	v_exp_f32_e32 v75, v64
	v_sub_f32_e32 v64, v76, v137
	v_cvt_pk_bf16_f32 v68, v72, v73
	v_add_f32_e32 v72, v72, v88
	v_mul_f32_e32 v48, 0x3fb8aa3b, v48
	v_mul_f32_e32 v64, 0x3d800000, v64
	v_add_f32_e32 v72, v73, v72
	v_exp_f32_e32 v73, v48
	v_sub_f32_e32 v48, v49, v137
	v_mul_f32_e32 v64, 0x3fb8aa3b, v64
	v_mul_f32_e32 v48, 0x3d800000, v48
	v_exp_f32_e32 v76, v64
	v_sub_f32_e32 v64, v77, v137
	v_mul_f32_e32 v48, 0x3fb8aa3b, v48
	v_mul_f32_e32 v64, 0x3d800000, v64
	v_cvt_pk_bf16_f32 v69, v74, v75
	v_add_f32_e32 v72, v74, v72
	v_exp_f32_e32 v74, v48
	v_sub_f32_e32 v48, v50, v137
	v_mul_f32_e32 v64, 0x3fb8aa3b, v64
	v_mul_f32_e32 v48, 0x3d800000, v48
	v_exp_f32_e32 v77, v64
	v_sub_f32_e32 v64, v78, v137
	v_mul_f32_e32 v48, 0x3fb8aa3b, v48
	v_mul_f32_e32 v64, 0x3d800000, v64
	v_add_f32_e32 v72, v75, v72
	v_exp_f32_e32 v75, v48
	v_sub_f32_e32 v48, v51, v137
	v_mul_f32_e32 v64, 0x3fb8aa3b, v64
	v_mul_f32_e32 v48, 0x3d800000, v48
	v_exp_f32_e32 v78, v64
	v_sub_f32_e32 v64, v79, v137
	v_mul_f32_e32 v48, 0x3fb8aa3b, v48
	v_mul_f32_e32 v64, 0x3d800000, v64
	v_cvt_pk_bf16_f32 v70, v76, v77
	v_add_f32_e32 v72, v76, v72
	v_exp_f32_e32 v76, v48
	v_sub_f32_e32 v48, v52, v137
	v_mul_f32_e32 v64, 0x3fb8aa3b, v64
	v_mul_f32_e32 v48, 0x3d800000, v48
	v_exp_f32_e32 v79, v64
; DI void phase_xattn(const Params& p) {
;     ...
; #pragma unroll
;     for (int kt = 0; kt < 8; ++kt) {
;       float pv[16];
; #pragma unroll
;       for (int i = 0; i < 16; ++i) { pv[i] = __expf((Sx[kt][i] - mx) * 0.0625f); ls += pv[i]; }
; #pragma unroll
;       for (int s = 0; s < 2; ++s) Pf[kt][s] = pack8(pv[8 * s], pv[8 * s + 1], pv[8 * s + 2], pv[8 * s + 3], pv[8 * s + 4], pv[8 * s + 5], pv[8 * s + 6], pv[8 * s + 7]);
;     }
	v_mul_f32_e32 v48, 0x3fb8aa3b, v48
	v_add_f32_e32 v72, v77, v72
	v_exp_f32_e32 v77, v48
	v_sub_f32_e32 v48, v53, v137
	v_mul_f32_e32 v48, 0x3d800000, v48
	v_mul_f32_e32 v48, 0x3fb8aa3b, v48
	v_cvt_pk_bf16_f32 v71, v78, v79
	v_add_f32_e32 v72, v78, v72
	v_exp_f32_e32 v78, v48
	v_sub_f32_e32 v48, v54, v137
	v_mul_f32_e32 v48, 0x3d800000, v48
	v_mul_f32_e32 v48, 0x3fb8aa3b, v48
	v_add_f32_e32 v72, v79, v72
	v_exp_f32_e32 v79, v48
	v_sub_f32_e32 v48, v55, v137
	v_mul_f32_e32 v48, 0x3d800000, v48
	v_mul_f32_e32 v48, 0x3fb8aa3b, v48
	v_exp_f32_e32 v88, v48
	v_sub_f32_e32 v48, v56, v137
	v_mul_f32_e32 v48, 0x3d800000, v48
	v_mul_f32_e32 v48, 0x3fb8aa3b, v48
	v_exp_f32_e32 v56, v48
	v_sub_f32_e32 v48, v57, v137
	v_mul_f32_e32 v48, 0x3d800000, v48
	v_add_f32_e32 v72, v73, v72
	v_mul_f32_e32 v48, 0x3fb8aa3b, v48
	v_add_f32_e32 v72, v74, v72
	v_exp_f32_e32 v57, v48
	v_sub_f32_e32 v48, v58, v137
	v_add_f32_e32 v72, v75, v72
	v_mul_f32_e32 v48, 0x3d800000, v48
	v_add_f32_e32 v72, v76, v72
	v_mul_f32_e32 v48, 0x3fb8aa3b, v48
	v_add_f32_e32 v72, v77, v72
	v_exp_f32_e32 v58, v48
	v_sub_f32_e32 v48, v59, v137
	v_add_f32_e32 v72, v78, v72
	v_mul_f32_e32 v48, 0x3d800000, v48
	v_add_f32_e32 v72, v79, v72
	v_sub_f32_e32 v32, v32, v137
	v_mul_f32_e32 v48, 0x3fb8aa3b, v48
	v_add_f32_e32 v72, v88, v72
	v_mul_f32_e32 v32, 0x3d800000, v32
	v_exp_f32_e32 v59, v48
	v_sub_f32_e32 v48, v60, v137
	v_cvt_pk_bf16_f32 v52, v56, v57
	v_add_f32_e32 v56, v56, v72
	v_mul_f32_e32 v32, 0x3fb8aa3b, v32
	v_mul_f32_e32 v48, 0x3d800000, v48
	v_add_f32_e32 v56, v57, v56
	v_exp_f32_e32 v57, v32
	v_sub_f32_e32 v32, v33, v137
	v_mul_f32_e32 v48, 0x3fb8aa3b, v48
	v_mul_f32_e32 v32, 0x3d800000, v32
	v_exp_f32_e32 v60, v48
	v_sub_f32_e32 v48, v61, v137
	v_mul_f32_e32 v32, 0x3fb8aa3b, v32
	v_mul_f32_e32 v48, 0x3d800000, v48
	v_cvt_pk_bf16_f32 v53, v58, v59
	v_add_f32_e32 v56, v58, v56
	v_exp_f32_e32 v58, v32
	v_sub_f32_e32 v32, v34, v137
	v_mul_f32_e32 v48, 0x3fb8aa3b, v48
	v_mul_f32_e32 v32, 0x3d800000, v32
	v_exp_f32_e32 v61, v48
	v_sub_f32_e32 v48, v62, v137
	v_mul_f32_e32 v32, 0x3fb8aa3b, v32
	v_mul_f32_e32 v48, 0x3d800000, v48
	v_add_f32_e32 v56, v59, v56
	v_exp_f32_e32 v59, v32
	v_sub_f32_e32 v32, v35, v137
	v_mul_f32_e32 v48, 0x3fb8aa3b, v48
	v_mul_f32_e32 v32, 0x3d800000, v32
	v_exp_f32_e32 v62, v48
	v_sub_f32_e32 v48, v63, v137
	v_mul_f32_e32 v32, 0x3fb8aa3b, v32
	v_mul_f32_e32 v48, 0x3d800000, v48
	v_cvt_pk_bf16_f32 v54, v60, v61
	v_add_f32_e32 v56, v60, v56
	v_exp_f32_e32 v60, v32
	v_sub_f32_e32 v32, v36, v137
	v_mul_f32_e32 v48, 0x3fb8aa3b, v48
	v_mul_f32_e32 v32, 0x3d800000, v32
	v_exp_f32_e32 v63, v48
	v_mul_f32_e32 v32, 0x3fb8aa3b, v32
	v_add_f32_e32 v56, v61, v56
	v_exp_f32_e32 v61, v32
	v_sub_f32_e32 v32, v37, v137
	v_mul_f32_e32 v32, 0x3d800000, v32
	v_mul_f32_e32 v32, 0x3fb8aa3b, v32
	v_cvt_pk_bf16_f32 v55, v62, v63
	v_add_f32_e32 v56, v62, v56
	v_exp_f32_e32 v62, v32
	v_sub_f32_e32 v32, v38, v137
	v_mul_f32_e32 v32, 0x3d800000, v32
	v_mul_f32_e32 v32, 0x3fb8aa3b, v32
	v_add_f32_e32 v56, v63, v56
	v_exp_f32_e32 v63, v32
	v_sub_f32_e32 v32, v39, v137
	v_mul_f32_e32 v32, 0x3d800000, v32
	v_mul_f32_e32 v32, 0x3fb8aa3b, v32
	v_exp_f32_e32 v72, v32
	v_sub_f32_e32 v32, v40, v137
	v_mul_f32_e32 v32, 0x3d800000, v32
	v_mul_f32_e32 v32, 0x3fb8aa3b, v32
	v_exp_f32_e32 v40, v32
	v_sub_f32_e32 v32, v41, v137
	v_mul_f32_e32 v32, 0x3d800000, v32
	v_add_f32_e32 v56, v57, v56
	v_mul_f32_e32 v32, 0x3fb8aa3b, v32
	v_add_f32_e32 v56, v58, v56
	v_exp_f32_e32 v41, v32
	v_sub_f32_e32 v32, v42, v137
	v_add_f32_e32 v56, v59, v56
	v_mul_f32_e32 v32, 0x3d800000, v32
	v_add_f32_e32 v56, v60, v56
	v_mul_f32_e32 v32, 0x3fb8aa3b, v32
	v_add_f32_e32 v56, v61, v56
	v_exp_f32_e32 v42, v32
	v_sub_f32_e32 v32, v43, v137
	v_add_f32_e32 v56, v62, v56
	v_mul_f32_e32 v32, 0x3d800000, v32
	v_add_f32_e32 v56, v63, v56
	v_sub_f32_e32 v16, v16, v137
	v_mul_f32_e32 v32, 0x3fb8aa3b, v32
	v_add_f32_e32 v56, v72, v56
	v_mul_f32_e32 v16, 0x3d800000, v16
	v_exp_f32_e32 v43, v32
	v_sub_f32_e32 v32, v44, v137
	v_cvt_pk_bf16_f32 v36, v40, v41
	v_add_f32_e32 v40, v40, v56
	v_mul_f32_e32 v16, 0x3fb8aa3b, v16
	v_mul_f32_e32 v32, 0x3d800000, v32
	v_add_f32_e32 v40, v41, v40
	v_exp_f32_e32 v41, v16
	v_sub_f32_e32 v16, v17, v137
	v_mul_f32_e32 v32, 0x3fb8aa3b, v32
	v_mul_f32_e32 v16, 0x3d800000, v16
	v_exp_f32_e32 v44, v32
	v_sub_f32_e32 v32, v45, v137
	v_mul_f32_e32 v16, 0x3fb8aa3b, v16
	v_mul_f32_e32 v32, 0x3d800000, v32
	v_cvt_pk_bf16_f32 v37, v42, v43
	v_add_f32_e32 v40, v42, v40
	v_exp_f32_e32 v42, v16
	v_sub_f32_e32 v16, v18, v137
	v_mul_f32_e32 v32, 0x3fb8aa3b, v32
	v_mul_f32_e32 v16, 0x3d800000, v16
	v_exp_f32_e32 v45, v32
	v_sub_f32_e32 v32, v46, v137
	v_mul_f32_e32 v16, 0x3fb8aa3b, v16
	v_mul_f32_e32 v32, 0x3d800000, v32
	v_add_f32_e32 v40, v43, v40
	v_exp_f32_e32 v43, v16
	v_sub_f32_e32 v16, v19, v137
	v_mul_f32_e32 v32, 0x3fb8aa3b, v32
	v_mul_f32_e32 v16, 0x3d800000, v16
	v_exp_f32_e32 v46, v32
	v_sub_f32_e32 v32, v47, v137
	v_mul_f32_e32 v16, 0x3fb8aa3b, v16
	v_mul_f32_e32 v32, 0x3d800000, v32
	v_cvt_pk_bf16_f32 v38, v44, v45
	v_add_f32_e32 v40, v44, v40
	v_exp_f32_e32 v44, v16
	v_sub_f32_e32 v16, v20, v137
	v_mul_f32_e32 v32, 0x3fb8aa3b, v32
	v_mul_f32_e32 v16, 0x3d800000, v16
	v_exp_f32_e32 v47, v32
	v_mul_f32_e32 v16, 0x3fb8aa3b, v16
	v_add_f32_e32 v40, v45, v40
	v_exp_f32_e32 v45, v16
	v_sub_f32_e32 v16, v21, v137
	v_mul_f32_e32 v16, 0x3d800000, v16
	v_mul_f32_e32 v16, 0x3fb8aa3b, v16
	v_cvt_pk_bf16_f32 v39, v46, v47
	v_add_f32_e32 v40, v46, v40
	v_exp_f32_e32 v46, v16
	v_sub_f32_e32 v16, v22, v137
	v_mul_f32_e32 v16, 0x3d800000, v16
	v_mul_f32_e32 v16, 0x3fb8aa3b, v16
	v_add_f32_e32 v40, v47, v40
; DI f32x16 zero16() { f32x16 z; for (int i = 0; i < 16; ++i) z[i] = 0.f; return z; }
; DI void phase_xattn(const Params& p) {
;     ...
; #pragma unroll
;     for (int kt = 0; kt < 8; ++kt) {
;       float pv[16];
; #pragma unroll
;       for (int i = 0; i < 16; ++i) { pv[i] = __expf((Sx[kt][i] - mx) * 0.0625f); ls += pv[i]; }
; #pragma unroll
;       for (int s = 0; s < 2; ++s) Pf[kt][s] = pack8(pv[8 * s], pv[8 * s + 1], pv[8 * s + 2], pv[8 * s + 3], pv[8 * s + 4], pv[8 * s + 5], pv[8 * s + 6], pv[8 * s + 7]);
;     }
;     ls += __shfl_xor(ls, 32);
;     const float inv = 1.f / ls;
; #pragma unroll 1
;     for (int dt = 0; dt < 8; ++dt) {
;       f32x16 o = zero16();
;       const u16* vrow = mv + ((((size_t)(b * 4 + h) * 8 + dt) * 8) * 2) * 512 + lane * 8;
	v_exp_f32_e32 v47, v16
	v_sub_f32_e32 v16, v23, v137
	v_mul_f32_e32 v16, 0x3d800000, v16
	v_mul_f32_e32 v16, 0x3fb8aa3b, v16
	v_exp_f32_e32 v56, v16
	v_sub_f32_e32 v16, v24, v137
	v_mul_f32_e32 v16, 0x3d800000, v16
	v_mul_f32_e32 v16, 0x3fb8aa3b, v16
	v_exp_f32_e32 v24, v16
	v_sub_f32_e32 v16, v25, v137
	v_mul_f32_e32 v16, 0x3d800000, v16
	v_mul_f32_e32 v16, 0x3fb8aa3b, v16
	v_exp_f32_e32 v25, v16
	v_sub_f32_e32 v16, v26, v137
	v_mul_f32_e32 v16, 0x3d800000, v16
	v_mul_f32_e32 v16, 0x3fb8aa3b, v16
	v_exp_f32_e32 v26, v16
	v_sub_f32_e32 v16, v27, v137
	v_mul_f32_e32 v16, 0x3d800000, v16
	v_mul_f32_e32 v16, 0x3fb8aa3b, v16
	v_exp_f32_e32 v27, v16
	v_sub_f32_e32 v16, v28, v137
	v_mul_f32_e32 v16, 0x3d800000, v16
	v_add_f32_e32 v40, v41, v40
	v_mul_f32_e32 v16, 0x3fb8aa3b, v16
	v_add_f32_e32 v40, v42, v40
	v_exp_f32_e32 v28, v16
	v_sub_f32_e32 v16, v29, v137
	v_add_f32_e32 v40, v43, v40
	v_mul_f32_e32 v16, 0x3d800000, v16
	v_add_f32_e32 v40, v44, v40
	v_mul_f32_e32 v16, 0x3fb8aa3b, v16
	v_add_f32_e32 v40, v45, v40
	v_exp_f32_e32 v29, v16
	v_sub_f32_e32 v16, v30, v137
	v_add_f32_e32 v40, v46, v40
	v_mul_f32_e32 v16, 0x3d800000, v16
	v_add_f32_e32 v40, v47, v40
	v_mul_f32_e32 v16, 0x3fb8aa3b, v16
	v_add_f32_e32 v40, v56, v40
	v_exp_f32_e32 v30, v16
	v_sub_f32_e32 v16, v31, v137
	v_cvt_pk_bf16_f32 v20, v24, v25
	v_add_f32_e32 v24, v24, v40
	v_mul_f32_e32 v16, 0x3d800000, v16
	v_add_f32_e32 v24, v25, v24
	v_sub_f32_e32 v0, v0, v137
	v_sub_f32_e32 v1, v1, v137
	v_mul_f32_e32 v16, 0x3fb8aa3b, v16
	v_add_f32_e32 v24, v26, v24
	v_mul_f32_e32 v0, 0x3d800000, v0
	v_mul_f32_e32 v1, 0x3d800000, v1
	v_exp_f32_e32 v31, v16
	v_add_f32_e32 v24, v27, v24
	v_mul_f32_e32 v0, 0x3fb8aa3b, v0
	v_mul_f32_e32 v1, 0x3fb8aa3b, v1
	v_sub_f32_e32 v2, v2, v137
	v_add_f32_e32 v24, v28, v24
	v_exp_f32_e32 v0, v0
	v_exp_f32_e32 v1, v1
	v_mul_f32_e32 v2, 0x3d800000, v2
	v_sub_f32_e32 v3, v3, v137
	v_add_f32_e32 v24, v29, v24
	v_mul_f32_e32 v2, 0x3fb8aa3b, v2
	v_mul_f32_e32 v3, 0x3d800000, v3
	v_sub_f32_e32 v4, v4, v137
	v_add_f32_e32 v24, v30, v24
	v_exp_f32_e32 v2, v2
	v_mul_f32_e32 v3, 0x3fb8aa3b, v3
	v_mul_f32_e32 v4, 0x3d800000, v4
	v_sub_f32_e32 v5, v5, v137
	v_add_f32_e32 v25, v31, v24
	v_exp_f32_e32 v3, v3
	v_mul_f32_e32 v4, 0x3fb8aa3b, v4
	v_mul_f32_e32 v5, 0x3d800000, v5
	v_sub_f32_e32 v6, v6, v137
	v_exp_f32_e32 v4, v4
	v_mul_f32_e32 v5, 0x3fb8aa3b, v5
	v_mul_f32_e32 v6, 0x3d800000, v6
	v_sub_f32_e32 v7, v7, v137
	v_cvt_pk_bf16_f32 v24, v0, v1
	v_add_f32_e32 v0, v0, v25
	v_exp_f32_e32 v5, v5
	v_mul_f32_e32 v6, 0x3fb8aa3b, v6
	v_mul_f32_e32 v7, 0x3d800000, v7
	v_sub_f32_e32 v8, v8, v137
	v_add_f32_e32 v0, v1, v0
	v_exp_f32_e32 v6, v6
	v_mul_f32_e32 v7, 0x3fb8aa3b, v7
	v_mul_f32_e32 v8, 0x3d800000, v8
	v_sub_f32_e32 v9, v9, v137
	v_add_f32_e32 v0, v2, v0
	v_exp_f32_e32 v7, v7
	v_mul_f32_e32 v8, 0x3fb8aa3b, v8
	v_mul_f32_e32 v9, 0x3d800000, v9
	v_sub_f32_e32 v10, v10, v137
	v_add_f32_e32 v0, v3, v0
	v_exp_f32_e32 v8, v8
	v_mul_f32_e32 v9, 0x3fb8aa3b, v9
	v_mul_f32_e32 v10, 0x3d800000, v10
	v_sub_f32_e32 v11, v11, v137
	v_add_f32_e32 v0, v4, v0
	v_exp_f32_e32 v9, v9
	v_mul_f32_e32 v10, 0x3fb8aa3b, v10
	v_mul_f32_e32 v11, 0x3d800000, v11
	v_sub_f32_e32 v12, v12, v137
	v_add_f32_e32 v0, v5, v0
	v_exp_f32_e32 v10, v10
	v_mul_f32_e32 v11, 0x3fb8aa3b, v11
	v_mul_f32_e32 v12, 0x3d800000, v12
	v_sub_f32_e32 v13, v13, v137
	v_add_f32_e32 v0, v6, v0
	v_exp_f32_e32 v11, v11
	v_mul_f32_e32 v12, 0x3fb8aa3b, v12
	v_mul_f32_e32 v13, 0x3d800000, v13
	v_sub_f32_e32 v14, v14, v137
	v_add_f32_e32 v0, v7, v0
	v_exp_f32_e32 v12, v12
	v_mul_f32_e32 v13, 0x3fb8aa3b, v13
	v_mul_f32_e32 v14, 0x3d800000, v14
	v_sub_f32_e32 v15, v15, v137
	v_add_f32_e32 v0, v8, v0
	v_exp_f32_e32 v13, v13
	v_mul_f32_e32 v14, 0x3fb8aa3b, v14
	v_mul_f32_e32 v15, 0x3d800000, v15
	v_add_f32_e32 v0, v9, v0
	v_exp_f32_e32 v14, v14
	v_mul_f32_e32 v15, 0x3fb8aa3b, v15
	v_add_f32_e32 v0, v10, v0
	v_exp_f32_e32 v15, v15
	v_add_f32_e32 v0, v11, v0
	v_add_f32_e32 v0, v12, v0
	v_add_f32_e32 v0, v13, v0
	v_add_f32_e32 v0, v14, v0
	v_add_f32_e32 v0, v15, v0
	ds_bpermute_b32 v1, v151, v0
	v_cvt_pk_bf16_f32 v25, v2, v3
	v_cvt_pk_bf16_f32 v21, v26, v27
	v_cvt_pk_bf16_f32 v26, v4, v5
	v_cvt_pk_bf16_f32 v113, v155, v156
	s_waitcnt lgkmcnt(0)
	v_add_f32_e32 v0, v0, v1
	v_div_scale_f32 v1, s[0:1], v0, v0, 1.0
	v_rcp_f32_e32 v2, v1
	v_cvt_pk_bf16_f32 v114, v157, v158
	v_cvt_pk_bf16_f32 v115, v159, v160
	v_cvt_pk_bf16_f32 v96, v121, v122
	v_fma_f32 v3, -v1, v2, 1.0
	v_fmac_f32_e32 v2, v3, v2
	v_div_scale_f32 v3, vcc, 1.0, v0, 1.0
	v_mul_f32_e32 v4, v3, v2
	v_fma_f32 v5, -v1, v4, v3
	v_fmac_f32_e32 v4, v5, v2
	v_fma_f32 v1, -v1, v4, v3
	v_div_fmas_f32 v1, v1, v2, v4
	v_div_fixup_f32 v40, v1, v0, 1.0
	v_lshl_or_b32 v0, v154, 12, v168
	v_lshl_add_u32 v0, v136, 5, v0
	v_ashrrev_i32_e32 v1, 31, v0
	v_lshlrev_b64 v[0:1], 11, v[0:1]
	v_lshl_add_u64 v[0:1], v[132:133], 0, v[0:1]
	v_cvt_pk_bf16_f32 v97, v123, v124
	v_cvt_pk_bf16_f32 v98, v125, v126
	v_cvt_pk_bf16_f32 v99, v127, v138
	v_cvt_pk_bf16_f32 v80, v105, v106
	v_cvt_pk_bf16_f32 v81, v107, v108
	v_cvt_pk_bf16_f32 v82, v109, v110
	v_cvt_pk_bf16_f32 v83, v111, v120
	v_cvt_pk_bf16_f32 v64, v89, v90
	v_cvt_pk_bf16_f32 v65, v91, v92
	v_cvt_pk_bf16_f32 v66, v93, v94
	v_cvt_pk_bf16_f32 v67, v95, v104
	v_cvt_pk_bf16_f32 v48, v73, v74
	v_cvt_pk_bf16_f32 v49, v75, v76
	v_cvt_pk_bf16_f32 v50, v77, v78
	v_cvt_pk_bf16_f32 v51, v79, v88
	v_cvt_pk_bf16_f32 v32, v57, v58
	v_cvt_pk_bf16_f32 v33, v59, v60
	v_cvt_pk_bf16_f32 v34, v61, v62
	v_cvt_pk_bf16_f32 v35, v63, v72
	v_cvt_pk_bf16_f32 v16, v41, v42
	v_cvt_pk_bf16_f32 v17, v43, v44
	v_cvt_pk_bf16_f32 v18, v45, v46
	v_cvt_pk_bf16_f32 v19, v47, v56
; #define MFMA(a, b, c) __builtin_amdgcn_mfma_f32_32x32x16_bf16((a), (b), (c), 0, 0, 0)
; DI f32x16 zero16() { f32x16 z; for (int i = 0; i < 16; ++i) z[i] = 0.f; return z; }
; DI void phase_xattn(const Params& p) {
;     ...
; #pragma unroll 1
;     for (int dt = 0; dt < 8; ++dt) {
;       f32x16 o = zero16();
;       const u16* vrow = mv + ((((size_t)(b * 4 + h) * 8 + dt) * 8) * 2) * 512 + lane * 8;
; #pragma unroll
;       for (int kt = 0; kt < 8; ++kt)
; #pragma unroll
;         for (int s = 0; s < 2; ++s) o = MFMA(ldg8(vrow + (kt * 2 + s) * 512), Pf[kt][s], o);
	v_cvt_pk_bf16_f32 v22, v28, v29
	v_cvt_pk_bf16_f32 v23, v30, v31
	v_cvt_pk_bf16_f32 v27, v6, v7
	v_cvt_pk_bf16_f32 v28, v8, v9
	v_cvt_pk_bf16_f32 v29, v10, v11
	v_cvt_pk_bf16_f32 v30, v12, v13
	v_cvt_pk_bf16_f32 v31, v14, v15
	v_mov_b32_e32 v41, v40
	v_lshl_add_u64 v[42:43], v[164:165], 0, v[134:135]
	v_lshl_add_u64 v[44:45], v[0:1], 0, v[128:129]
	s_add_u32 s100, s96, 0xa000000
	s_addc_u32 s101, s97, 0
	v_mov_b32_e32 v154, v42
	v_add_u32_e32 v155, 0x1000, v42
	v_add_u32_e32 v156, 0x2000, v42
	v_add_u32_e32 v157, 0x3000, v42
	global_load_dwordx4 v[180:183], v154, s[100:101]
	global_load_dwordx4 v[184:187], v154, s[100:101] offset:1024
	global_load_dwordx4 v[188:191], v154, s[100:101] offset:2048
	global_load_dwordx4 v[192:195], v154, s[100:101] offset:3072
	global_load_dwordx4 v[196:199], v155, s[100:101]
	global_load_dwordx4 v[200:203], v155, s[100:101] offset:1024
	global_load_dwordx4 v[212:215], v155, s[100:101] offset:2048
	global_load_dwordx4 v[216:219], v155, s[100:101] offset:3072
	global_load_dwordx4 v[220:223], v156, s[100:101]
	global_load_dwordx4 v[224:227], v156, s[100:101] offset:1024
	global_load_dwordx4 v[228:231], v156, s[100:101] offset:2048
	global_load_dwordx4 v[232:235], v156, s[100:101] offset:3072
	global_load_dwordx4 v[236:239], v157, s[100:101]
	global_load_dwordx4 v[240:243], v157, s[100:101] offset:1024
	global_load_dwordx4 v[244:247], v157, s[100:101] offset:2048
	global_load_dwordx4 v[248:251], v157, s[100:101] offset:3072
	s_mov_b32 s0, 7
; #define MFMA(a, b, c) __builtin_amdgcn_mfma_f32_32x32x16_bf16((a), (b), (c), 0, 0, 0)
; DI f32x16 zero16() { f32x16 z; for (int i = 0; i < 16; ++i) z[i] = 0.f; return z; }
; DI void phase_xattn(const Params& p) {
;     ...
; #pragma unroll 1
;     for (int dt = 0; dt < 8; ++dt) {
;       f32x16 o = zero16();
;       const u16* vrow = mv + ((((size_t)(b * 4 + h) * 8 + dt) * 8) * 2) * 512 + lane * 8;
; #pragma unroll
;       for (int kt = 0; kt < 8; ++kt)
; #pragma unroll
;         for (int s = 0; s < 2; ++s) o = MFMA(ldg8(vrow + (kt * 2 + s) * 512), Pf[kt][s], o);
; #pragma unroll
;       for (int g = 0; g < 4; ++g)
;         st4bf(ox + (size_t)tok * 1024 + h * 256 + dt * 32 + 8 * g + 4 * lh, o[4 * g] * inv, o[4 * g + 1] * inv, o[4 * g + 2] * inv, o[4 * g + 3] * inv);
;     }
.LBB0_737:
	v_add_u32_e32 v158, 0x4000, v154
	v_add_u32_e32 v159, 0x4000, v155
	v_add_u32_e32 v160, 0x4000, v156
	v_add_u32_e32 v161, 0x4000, v157
	s_waitcnt vmcnt(15)
	v_mfma_f32_32x32x16_bf16 v[0:15], v[180:183], v[112:115], 0
	global_load_dwordx4 v[180:183], v158, s[100:101]
	s_waitcnt vmcnt(15)
	v_mfma_f32_32x32x16_bf16 v[0:15], v[184:187], v[116:119], v[0:15]
	global_load_dwordx4 v[184:187], v158, s[100:101] offset:1024
	s_waitcnt vmcnt(15)
	v_mfma_f32_32x32x16_bf16 v[0:15], v[188:191], v[96:99], v[0:15]
	global_load_dwordx4 v[188:191], v158, s[100:101] offset:2048
	s_waitcnt vmcnt(15)
	v_mfma_f32_32x32x16_bf16 v[0:15], v[192:195], v[100:103], v[0:15]
	global_load_dwordx4 v[192:195], v158, s[100:101] offset:3072
	s_waitcnt vmcnt(15)
	v_mfma_f32_32x32x16_bf16 v[0:15], v[196:199], v[80:83], v[0:15]
	global_load_dwordx4 v[196:199], v159, s[100:101]
	s_waitcnt vmcnt(15)
	v_mfma_f32_32x32x16_bf16 v[0:15], v[200:203], v[84:87], v[0:15]
	global_load_dwordx4 v[200:203], v159, s[100:101] offset:1024
	s_waitcnt vmcnt(15)
	v_mfma_f32_32x32x16_bf16 v[0:15], v[212:215], v[64:67], v[0:15]
	global_load_dwordx4 v[212:215], v159, s[100:101] offset:2048
	s_waitcnt vmcnt(15)
	v_mfma_f32_32x32x16_bf16 v[0:15], v[216:219], v[68:71], v[0:15]
	global_load_dwordx4 v[216:219], v159, s[100:101] offset:3072
	s_waitcnt vmcnt(15)
	v_mfma_f32_32x32x16_bf16 v[0:15], v[220:223], v[48:51], v[0:15]
	global_load_dwordx4 v[220:223], v160, s[100:101]
	s_waitcnt vmcnt(15)
	v_mfma_f32_32x32x16_bf16 v[0:15], v[224:227], v[52:55], v[0:15]
	global_load_dwordx4 v[224:227], v160, s[100:101] offset:1024
	s_waitcnt vmcnt(15)
	v_mfma_f32_32x32x16_bf16 v[0:15], v[228:231], v[32:35], v[0:15]
	global_load_dwordx4 v[228:231], v160, s[100:101] offset:2048
	s_waitcnt vmcnt(15)
	v_mfma_f32_32x32x16_bf16 v[0:15], v[232:235], v[36:39], v[0:15]
	global_load_dwordx4 v[232:235], v160, s[100:101] offset:3072
	s_waitcnt vmcnt(15)
	v_mfma_f32_32x32x16_bf16 v[0:15], v[236:239], v[16:19], v[0:15]
	global_load_dwordx4 v[236:239], v161, s[100:101]
	s_waitcnt vmcnt(15)
	v_mfma_f32_32x32x16_bf16 v[0:15], v[240:243], v[20:23], v[0:15]
	global_load_dwordx4 v[240:243], v161, s[100:101] offset:1024
	s_waitcnt vmcnt(15)
	v_mfma_f32_32x32x16_bf16 v[0:15], v[244:247], v[24:27], v[0:15]
	global_load_dwordx4 v[244:247], v161, s[100:101] offset:2048
	s_waitcnt vmcnt(15)
	v_mfma_f32_32x32x16_bf16 v[0:15], v[248:251], v[28:31], v[0:15]
	global_load_dwordx4 v[248:251], v161, s[100:101] offset:3072
	v_mov_b32_e32 v154, v158
	v_mov_b32_e32 v155, v159
	v_mov_b32_e32 v156, v160
	v_mov_b32_e32 v157, v161
	v_lshl_add_u64 v[46:47], s[96:97], 0, v[44:45]
	v_lshl_add_u64 v[44:45], v[44:45], 0, 64
	s_nop 9
	v_pk_mul_f32 v[0:1], v[40:41], v[0:1]
	v_pk_mul_f32 v[2:3], v[40:41], v[2:3]
	v_pk_mul_f32 v[4:5], v[40:41], v[4:5]
	v_pk_mul_f32 v[6:7], v[40:41], v[6:7]
	v_pk_mul_f32 v[8:9], v[40:41], v[8:9]
	v_pk_mul_f32 v[10:11], v[40:41], v[10:11]
	v_pk_mul_f32 v[12:13], v[40:41], v[12:13]
	v_pk_mul_f32 v[14:15], v[40:41], v[14:15]
	v_cvt_pk_bf16_f32 v0, v0, v1
	v_cvt_pk_bf16_f32 v1, v2, v3
	v_cvt_pk_bf16_f32 v2, v4, v5
	v_cvt_pk_bf16_f32 v3, v6, v7
	v_cvt_pk_bf16_f32 v4, v8, v9
	v_cvt_pk_bf16_f32 v5, v10, v11
	v_cvt_pk_bf16_f32 v6, v12, v13
	v_cvt_pk_bf16_f32 v7, v14, v15
	global_store_dwordx2 v[46:47], v[0:1], off offset:-32
	global_store_dwordx2 v[46:47], v[2:3], off offset:-16
	global_store_dwordx2 v[46:47], v[4:5], off
	global_store_dwordx2 v[46:47], v[6:7], off offset:16
	s_add_i32 s0, s0, -1
	s_cmp_eq_u32 s0, 0
	s_cbranch_scc0 .LBB0_737
	s_waitcnt vmcnt(19)
	v_mfma_f32_32x32x16_bf16 v[0:15], v[180:183], v[112:115], 0
	s_waitcnt vmcnt(18)
	v_mfma_f32_32x32x16_bf16 v[0:15], v[184:187], v[116:119], v[0:15]
	s_waitcnt vmcnt(17)
	v_mfma_f32_32x32x16_bf16 v[0:15], v[188:191], v[96:99], v[0:15]
	s_waitcnt vmcnt(16)
	v_mfma_f32_32x32x16_bf16 v[0:15], v[192:195], v[100:103], v[0:15]
	s_waitcnt vmcnt(15)
	v_mfma_f32_32x32x16_bf16 v[0:15], v[196:199], v[80:83], v[0:15]
	s_waitcnt vmcnt(14)
	v_mfma_f32_32x32x16_bf16 v[0:15], v[200:203], v[84:87], v[0:15]
	s_waitcnt vmcnt(13)
	v_mfma_f32_32x32x16_bf16 v[0:15], v[212:215], v[64:67], v[0:15]
	s_waitcnt vmcnt(12)
	v_mfma_f32_32x32x16_bf16 v[0:15], v[216:219], v[68:71], v[0:15]
	s_waitcnt vmcnt(11)
	v_mfma_f32_32x32x16_bf16 v[0:15], v[220:223], v[48:51], v[0:15]
	s_waitcnt vmcnt(10)
	v_mfma_f32_32x32x16_bf16 v[0:15], v[224:227], v[52:55], v[0:15]
	s_waitcnt vmcnt(9)
	v_mfma_f32_32x32x16_bf16 v[0:15], v[228:231], v[32:35], v[0:15]
	s_waitcnt vmcnt(8)
	v_mfma_f32_32x32x16_bf16 v[0:15], v[232:235], v[36:39], v[0:15]
	s_waitcnt vmcnt(7)
	v_mfma_f32_32x32x16_bf16 v[0:15], v[236:239], v[16:19], v[0:15]
	s_waitcnt vmcnt(6)
	v_mfma_f32_32x32x16_bf16 v[0:15], v[240:243], v[20:23], v[0:15]
	s_waitcnt vmcnt(5)
	v_mfma_f32_32x32x16_bf16 v[0:15], v[244:247], v[24:27], v[0:15]
	s_waitcnt vmcnt(4)
	v_mfma_f32_32x32x16_bf16 v[0:15], v[248:251], v[28:31], v[0:15]
	s_nop 1
	v_lshl_add_u64 v[46:47], s[96:97], 0, v[44:45]
	v_lshl_add_u64 v[44:45], v[44:45], 0, 64
	s_nop 9
	v_pk_mul_f32 v[0:1], v[40:41], v[0:1]
	v_pk_mul_f32 v[2:3], v[40:41], v[2:3]
	v_pk_mul_f32 v[4:5], v[40:41], v[4:5]
	v_pk_mul_f32 v[6:7], v[40:41], v[6:7]
	v_pk_mul_f32 v[8:9], v[40:41], v[8:9]
	v_pk_mul_f32 v[10:11], v[40:41], v[10:11]
	v_pk_mul_f32 v[12:13], v[40:41], v[12:13]
	v_pk_mul_f32 v[14:15], v[40:41], v[14:15]
	v_cvt_pk_bf16_f32 v0, v0, v1
	v_cvt_pk_bf16_f32 v1, v2, v3
	v_cvt_pk_bf16_f32 v2, v4, v5
	v_cvt_pk_bf16_f32 v3, v6, v7
	v_cvt_pk_bf16_f32 v4, v8, v9
	v_cvt_pk_bf16_f32 v5, v10, v11
	v_cvt_pk_bf16_f32 v6, v12, v13
	v_cvt_pk_bf16_f32 v7, v14, v15
	global_store_dwordx2 v[46:47], v[0:1], off offset:-32
	global_store_dwordx2 v[46:47], v[2:3], off offset:-16
	global_store_dwordx2 v[46:47], v[4:5], off
	global_store_dwordx2 v[46:47], v[6:7], off offset:16
	v_add_u32_e32 v153, s3, v153
	v_cmp_lt_i32_e32 vcc, s30, v153
	s_or_b64 s[14:15], vcc, s[14:15]
	s_andn2_b64 exec, exec, s[14:15]
	s_cbranch_execnz .LBB0_734

; #define MFMA(a, b, c) __builtin_amdgcn_mfma_f32_32x32x16_bf16((a), (b), (c), 0, 0, 0)
; DI int crow(int i, int h) { return (i & 3) + 8 * (i >> 2) + 4 * h; }
; DI f32x16 zero16() { f32x16 z; for (int i = 0; i < 16; ++i) z[i] = 0.f; return z; }
; DI void peer_topk_item(const Params& p, int tt128, int head, char* smem) {
;     ...
; #pragma unroll 1
;     for (int tt = 0; tt < 4; ++tt) {
;       f32x16 acc = zero16();
;       const u16* brow = pq + (((((size_t)(tok0 >> 5) + tt) * 8 + head) * 2 + half) * 8) * 512 + lane * 8;
; #pragma unroll
;       for (int ks = 0; ks < 8; ++ks) acc = MFMA(af[ks], ldg8(brow + ks * 512), acc);
; #pragma unroll
;       for (int i = 0; i < 16; ++i) sc[(half * 128 + tt * 32 + lr) * 129 + kt * 32 + crow(i, lh)] = acc[i];
;     }
.LBB0_964:
	s_mov_b32 s4, 0x16800000
	s_mov_b32 s5, 0
	s_mov_b64 s[8:9], 0x20000
	v_lshl_add_u64 v[142:143], v[52:53], 0, s[4:5]
	s_movk_i32 s10, 0x1000
	s_mov_b32 s11, 0
	v_lshl_add_u64 v[144:145], v[142:143], 0, s[10:11]
	v_lshl_add_u64 v[146:147], v[142:143], 0, s[8:9]
	v_lshl_add_u64 v[148:149], v[144:145], 0, s[8:9]
	v_lshl_add_u64 v[150:151], v[146:147], 0, s[8:9]
	v_lshl_add_u64 v[152:153], v[148:149], 0, s[8:9]
	v_lshl_add_u64 v[154:155], v[150:151], 0, s[8:9]
	v_lshl_add_u64 v[156:157], v[152:153], 0, s[8:9]
	global_load_dwordx4 v[168:171], v[142:143], off
	global_load_dwordx4 v[172:175], v[142:143], off offset:1024
	global_load_dwordx4 v[176:179], v[142:143], off offset:2048
	global_load_dwordx4 v[180:183], v[142:143], off offset:3072
	global_load_dwordx4 v[184:187], v[144:145], off
	global_load_dwordx4 v[188:191], v[144:145], off offset:1024
	global_load_dwordx4 v[192:195], v[144:145], off offset:2048
	global_load_dwordx4 v[196:199], v[144:145], off offset:3072
	global_load_dwordx4 v[200:203], v[146:147], off
	global_load_dwordx4 v[204:207], v[146:147], off offset:1024
	global_load_dwordx4 v[208:211], v[146:147], off offset:2048
	global_load_dwordx4 v[212:215], v[146:147], off offset:3072
	global_load_dwordx4 v[216:219], v[148:149], off
	global_load_dwordx4 v[220:223], v[148:149], off offset:1024
	global_load_dwordx4 v[224:227], v[148:149], off offset:2048
	global_load_dwordx4 v[228:231], v[148:149], off offset:3072
	s_waitcnt vmcnt(15)
	v_mfma_f32_32x32x16_bf16 v[0:15], v[16:19], v[168:171], 0
	global_load_dwordx4 v[168:171], v[150:151], off
	s_waitcnt vmcnt(15)
	v_mfma_f32_32x32x16_bf16 v[0:15], v[20:23], v[172:175], v[0:15]
	global_load_dwordx4 v[172:175], v[150:151], off offset:1024
	s_waitcnt vmcnt(15)
	v_mfma_f32_32x32x16_bf16 v[0:15], v[24:27], v[176:179], v[0:15]
	global_load_dwordx4 v[176:179], v[150:151], off offset:2048
	s_waitcnt vmcnt(15)
	v_mfma_f32_32x32x16_bf16 v[0:15], v[28:31], v[180:183], v[0:15]
	global_load_dwordx4 v[180:183], v[150:151], off offset:3072
	s_waitcnt vmcnt(15)
	v_mfma_f32_32x32x16_bf16 v[0:15], v[32:35], v[184:187], v[0:15]
	global_load_dwordx4 v[184:187], v[152:153], off
	s_waitcnt vmcnt(15)
	v_mfma_f32_32x32x16_bf16 v[0:15], v[36:39], v[188:191], v[0:15]
	global_load_dwordx4 v[188:191], v[152:153], off offset:1024
	s_waitcnt vmcnt(15)
	v_mfma_f32_32x32x16_bf16 v[0:15], v[40:43], v[192:195], v[0:15]
	global_load_dwordx4 v[192:195], v[152:153], off offset:2048
	s_waitcnt vmcnt(15)
	v_mfma_f32_32x32x16_bf16 v[0:15], v[44:47], v[196:199], v[0:15]
	global_load_dwordx4 v[196:199], v[152:153], off offset:3072
	s_nop 11
	ds_write2_b32 v124, v0, v1 offset1:1
	ds_write2_b32 v124, v2, v3 offset0:2 offset1:3
	ds_write2_b32 v124, v4, v5 offset0:8 offset1:9
	ds_write2_b32 v124, v6, v7 offset0:10 offset1:11
	ds_write2_b32 v124, v8, v9 offset0:16 offset1:17
	ds_write2_b32 v124, v10, v11 offset0:18 offset1:19
	ds_write2_b32 v124, v12, v13 offset0:24 offset1:25
	ds_write2_b32 v124, v14, v15 offset0:26 offset1:27
	v_add_u32_e32 v124, 0x4080, v124
	s_waitcnt vmcnt(15)
	v_mfma_f32_32x32x16_bf16 v[0:15], v[16:19], v[200:203], 0
	global_load_dwordx4 v[200:203], v[154:155], off
	s_waitcnt vmcnt(15)
	v_mfma_f32_32x32x16_bf16 v[0:15], v[20:23], v[204:207], v[0:15]
	global_load_dwordx4 v[204:207], v[154:155], off offset:1024
	s_waitcnt vmcnt(15)
	v_mfma_f32_32x32x16_bf16 v[0:15], v[24:27], v[208:211], v[0:15]
	global_load_dwordx4 v[208:211], v[154:155], off offset:2048
	s_waitcnt vmcnt(15)
	v_mfma_f32_32x32x16_bf16 v[0:15], v[28:31], v[212:215], v[0:15]
	global_load_dwordx4 v[212:215], v[154:155], off offset:3072
	s_waitcnt vmcnt(15)
	v_mfma_f32_32x32x16_bf16 v[0:15], v[32:35], v[216:219], v[0:15]
	global_load_dwordx4 v[216:219], v[156:157], off
	s_waitcnt vmcnt(15)
	v_mfma_f32_32x32x16_bf16 v[0:15], v[36:39], v[220:223], v[0:15]
	global_load_dwordx4 v[220:223], v[156:157], off offset:1024
	s_waitcnt vmcnt(15)
	v_mfma_f32_32x32x16_bf16 v[0:15], v[40:43], v[224:227], v[0:15]
	global_load_dwordx4 v[224:227], v[156:157], off offset:2048
	s_waitcnt vmcnt(15)
	v_mfma_f32_32x32x16_bf16 v[0:15], v[44:47], v[228:231], v[0:15]
	global_load_dwordx4 v[228:231], v[156:157], off offset:3072
	s_nop 11
	ds_write2_b32 v124, v0, v1 offset1:1
	ds_write2_b32 v124, v2, v3 offset0:2 offset1:3
	ds_write2_b32 v124, v4, v5 offset0:8 offset1:9
	ds_write2_b32 v124, v6, v7 offset0:10 offset1:11
	ds_write2_b32 v124, v8, v9 offset0:16 offset1:17
	ds_write2_b32 v124, v10, v11 offset0:18 offset1:19
	ds_write2_b32 v124, v12, v13 offset0:24 offset1:25
	ds_write2_b32 v124, v14, v15 offset0:26 offset1:27
	v_add_u32_e32 v124, 0x4080, v124
	s_waitcnt vmcnt(15)
	v_mfma_f32_32x32x16_bf16 v[0:15], v[16:19], v[168:171], 0
	s_waitcnt vmcnt(14)
	v_mfma_f32_32x32x16_bf16 v[0:15], v[20:23], v[172:175], v[0:15]
	s_waitcnt vmcnt(13)
	v_mfma_f32_32x32x16_bf16 v[0:15], v[24:27], v[176:179], v[0:15]
	s_waitcnt vmcnt(12)
	v_mfma_f32_32x32x16_bf16 v[0:15], v[28:31], v[180:183], v[0:15]
	s_waitcnt vmcnt(11)
	v_mfma_f32_32x32x16_bf16 v[0:15], v[32:35], v[184:187], v[0:15]
	s_waitcnt vmcnt(10)
	v_mfma_f32_32x32x16_bf16 v[0:15], v[36:39], v[188:191], v[0:15]
	s_waitcnt vmcnt(9)
	v_mfma_f32_32x32x16_bf16 v[0:15], v[40:43], v[192:195], v[0:15]
	s_waitcnt vmcnt(8)
	v_mfma_f32_32x32x16_bf16 v[0:15], v[44:47], v[196:199], v[0:15]
	s_nop 11
	ds_write2_b32 v124, v0, v1 offset1:1
	ds_write2_b32 v124, v2, v3 offset0:2 offset1:3
	ds_write2_b32 v124, v4, v5 offset0:8 offset1:9
	ds_write2_b32 v124, v6, v7 offset0:10 offset1:11
	ds_write2_b32 v124, v8, v9 offset0:16 offset1:17
	ds_write2_b32 v124, v10, v11 offset0:18 offset1:19
	ds_write2_b32 v124, v12, v13 offset0:24 offset1:25
	ds_write2_b32 v124, v14, v15 offset0:26 offset1:27
	v_add_u32_e32 v124, 0x4080, v124
	s_waitcnt vmcnt(7)
	v_mfma_f32_32x32x16_bf16 v[0:15], v[16:19], v[200:203], 0
	s_waitcnt vmcnt(6)
	v_mfma_f32_32x32x16_bf16 v[0:15], v[20:23], v[204:207], v[0:15]
	s_waitcnt vmcnt(5)
	v_mfma_f32_32x32x16_bf16 v[0:15], v[24:27], v[208:211], v[0:15]
	s_waitcnt vmcnt(4)
	v_mfma_f32_32x32x16_bf16 v[0:15], v[28:31], v[212:215], v[0:15]
	s_waitcnt vmcnt(3)
	v_mfma_f32_32x32x16_bf16 v[0:15], v[32:35], v[216:219], v[0:15]
	s_waitcnt vmcnt(2)
	v_mfma_f32_32x32x16_bf16 v[0:15], v[36:39], v[220:223], v[0:15]
	s_waitcnt vmcnt(1)
	v_mfma_f32_32x32x16_bf16 v[0:15], v[40:43], v[224:227], v[0:15]
	s_waitcnt vmcnt(0)
	v_mfma_f32_32x32x16_bf16 v[0:15], v[44:47], v[228:231], v[0:15]
	s_nop 11
	ds_write2_b32 v124, v0, v1 offset1:1
	ds_write2_b32 v124, v2, v3 offset0:2 offset1:3
	ds_write2_b32 v124, v4, v5 offset0:8 offset1:9
	ds_write2_b32 v124, v6, v7 offset0:10 offset1:11
	ds_write2_b32 v124, v8, v9 offset0:16 offset1:17
	ds_write2_b32 v124, v10, v11 offset0:18 offset1:19
	ds_write2_b32 v124, v12, v13 offset0:24 offset1:25
	ds_write2_b32 v124, v14, v15 offset0:26 offset1:27
	v_add_u32_e32 v124, 0x4080, v124
	s_mov_b64 s[0:1], 0x80000
	s_waitcnt lgkmcnt(0)
	s_barrier
; DI void peer_topk_item(const Params& p, int tt128, int head, char* smem) {
;     ...
;   if (tid < 256) {
;     float* row = sc + tid * 129;
;     float gm[8]; int gi[8];
; #pragma unroll
;     for (int g = 0; g < 8; ++g) {
;       float m = -INFINITY; int mi = g * 16;
; #pragma unroll
;       for (int j = 0; j < 16; ++j) { float v = row[g * 16 + j]; if (v > m) { m = v; mi = g * 16 + j; } }
;       gm[g] = m; gi[g] = mi;
;     }
	s_mov_b64 s[52:53], exec
	v_readlane_b32 s0, v255, 45
	v_readlane_b32 s1, v255, 46
	s_and_b64 s[0:1], s[52:53], s[0:1]
	s_mov_b64 exec, s[0:1]
	s_cbranch_execz .LBB0_968
	ds_read2_b32 v[0:1], v54 offset1:1
	ds_read2_b32 v[2:3], v54 offset0:2 offset1:3
	ds_read2_b32 v[4:5], v54 offset0:4 offset1:5
	ds_read2_b32 v[6:7], v54 offset0:6 offset1:7
	s_mov_b32 s4, 0
	s_waitcnt lgkmcnt(3)
	v_max_f32_e32 v0, v0, v0
	v_max_f32_e32 v0, 0xff800000, v0
	v_cmp_gt_f32_e32 vcc, v1, v0
	s_nop 1
	v_cndmask_b32_e32 v0, v0, v1, vcc
	v_cndmask_b32_e64 v8, 0, 1, vcc
	s_waitcnt lgkmcnt(2)
	v_cmp_gt_f32_e32 vcc, v2, v0
	s_nop 1
	v_cndmask_b32_e32 v0, v0, v2, vcc
	v_cndmask_b32_e64 v1, v8, 2, vcc
	v_cmp_gt_f32_e32 vcc, v3, v0
	s_nop 1
	v_cndmask_b32_e32 v0, v0, v3, vcc
	v_cndmask_b32_e64 v1, v1, 3, vcc
	s_waitcnt lgkmcnt(1)
	v_cmp_gt_f32_e32 vcc, v4, v0
	s_nop 1
	v_cndmask_b32_e64 v16, v1, 4, vcc
	v_cndmask_b32_e32 v2, v0, v4, vcc
	ds_read2_b32 v[0:1], v54 offset0:16 offset1:17
	v_cmp_gt_f32_e32 vcc, v5, v2
	s_waitcnt lgkmcnt(0)
	v_max_f32_e32 v0, v0, v0
	v_cndmask_b32_e32 v12, v2, v5, vcc
	ds_read2_b32 v[2:3], v54 offset0:18 offset1:19
	ds_read2_b32 v[4:5], v54 offset0:20 offset1:21
	ds_read2_b32 v[8:9], v54 offset0:22 offset1:23
	v_max_f32_e32 v0, 0xff800000, v0
	v_cmp_gt_f32_e64 s[0:1], v1, v0
	v_cmp_gt_f32_e64 s[8:9], v6, v12
	s_nop 0
	v_cndmask_b32_e64 v0, v0, v1, s[0:1]
	v_cndmask_b32_e64 v10, 16, 17, s[0:1]
	s_waitcnt lgkmcnt(2)
	v_cmp_gt_f32_e64 s[0:1], v2, v0
	v_cndmask_b32_e64 v6, v12, v6, s[8:9]
	v_cmp_gt_f32_e64 s[12:13], v7, v6
	v_cndmask_b32_e64 v0, v0, v2, s[0:1]
	v_cndmask_b32_e64 v1, v10, 18, s[0:1]
	v_cmp_gt_f32_e64 s[0:1], v3, v0
	v_cndmask_b32_e64 v12, v6, v7, s[12:13]
	s_nop 0
	v_cndmask_b32_e64 v0, v0, v3, s[0:1]
	v_cndmask_b32_e64 v1, v1, 19, s[0:1]
	s_waitcnt lgkmcnt(1)
	v_cmp_gt_f32_e64 s[0:1], v4, v0
	s_nop 1
	v_cndmask_b32_e64 v0, v0, v4, s[0:1]
	v_cndmask_b32_e64 v17, v1, 20, s[0:1]
	v_cmp_gt_f32_e64 s[0:1], v5, v0
	s_nop 1
	v_cndmask_b32_e64 v13, v0, v5, s[0:1]
	ds_read2_b32 v[0:1], v54 offset0:8 offset1:9
	ds_read2_b32 v[2:3], v54 offset0:10 offset1:11
	ds_read2_b32 v[4:5], v54 offset0:12 offset1:13
	ds_read2_b32 v[10:11], v54 offset0:14 offset1:15
	ds_read2_b32 v[6:7], v54 offset0:24 offset1:25
	s_waitcnt lgkmcnt(5)
	v_cmp_gt_f32_e64 s[10:11], v8, v13
	s_waitcnt lgkmcnt(4)
	v_cmp_gt_f32_e64 s[16:17], v0, v12
	v_cndmask_b32_e64 v8, v13, v8, s[10:11]
	v_cmp_gt_f32_e64 s[14:15], v9, v8
	v_cndmask_b32_e64 v0, v12, v0, s[16:17]
	v_cmp_gt_f32_e64 s[20:21], v1, v0
	v_cndmask_b32_e64 v18, v8, v9, s[14:15]
	s_waitcnt lgkmcnt(0)
	v_cmp_gt_f32_e64 s[18:19], v6, v18
	ds_read2_b32 v[8:9], v54 offset0:26 offset1:27
	ds_read2_b32 v[12:13], v54 offset0:28 offset1:29
	ds_read2_b32 v[14:15], v54 offset0:30 offset1:31
	v_cndmask_b32_e64 v6, v18, v6, s[18:19]
	v_cndmask_b32_e64 v0, v0, v1, s[20:21]
	v_cmp_gt_f32_e64 s[22:23], v7, v6
	v_cmp_gt_f32_e64 s[24:25], v2, v0
	s_nop 0
	v_cndmask_b32_e64 v1, v6, v7, s[22:23]
	v_cndmask_b32_e64 v0, v0, v2, s[24:25]
	s_waitcnt lgkmcnt(2)
	v_cmp_gt_f32_e64 s[26:27], v8, v1
	v_cmp_gt_f32_e64 s[28:29], v3, v0
	s_nop 0
	v_cndmask_b32_e64 v1, v1, v8, s[26:27]
	v_cndmask_b32_e64 v0, v0, v3, s[28:29]
	v_cmp_gt_f32_e64 s[30:31], v9, v1
	v_cmp_gt_f32_e64 s[34:35], v4, v0
	s_nop 0
	v_cndmask_b32_e64 v1, v1, v9, s[30:31]
	v_cndmask_b32_e64 v0, v0, v4, s[34:35]
	s_waitcnt lgkmcnt(1)
	v_cmp_gt_f32_e64 s[36:37], v12, v1
	v_cmp_gt_f32_e64 s[38:39], v5, v0
	s_nop 0
	v_cndmask_b32_e64 v1, v1, v12, s[36:37]
	v_cndmask_b32_e64 v0, v0, v5, s[38:39]
	v_cmp_gt_f32_e64 s[40:41], v13, v1
	v_cmp_gt_f32_e64 s[42:43], v10, v0
	s_nop 0
	v_cndmask_b32_e64 v1, v1, v13, s[40:41]
	v_cndmask_b32_e64 v2, v0, v10, s[42:43]
	s_waitcnt lgkmcnt(0)
	v_cmp_gt_f32_e64 s[44:45], v14, v1
	v_cndmask_b32_e64 v0, v16, 5, vcc
	v_cndmask_b32_e64 v0, v0, 6, s[8:9]
	v_cndmask_b32_e64 v3, v1, v14, s[44:45]
	v_cndmask_b32_e64 v1, v17, 21, s[0:1]
	v_cndmask_b32_e64 v1, v1, 22, s[10:11]
	v_cndmask_b32_e64 v0, v0, 7, s[12:13]
	v_cndmask_b32_e64 v1, v1, 23, s[14:15]
	v_cndmask_b32_e64 v0, v0, 8, s[16:17]
	v_cndmask_b32_e64 v1, v1, 24, s[18:19]
	v_cndmask_b32_e64 v0, v0, 9, s[20:21]
	v_cndmask_b32_e64 v1, v1, 25, s[22:23]
	v_cndmask_b32_e64 v0, v0, 10, s[24:25]
	v_cndmask_b32_e64 v1, v1, 26, s[26:27]
	v_cndmask_b32_e64 v0, v0, 11, s[28:29]
	v_cmp_gt_f32_e32 vcc, v11, v2
	v_cndmask_b32_e64 v1, v1, 27, s[30:31]
	v_cndmask_b32_e64 v0, v0, 12, s[34:35]
	v_cndmask_b32_e32 v2, v2, v11, vcc
	ds_read2_b32 v[4:5], v54 offset0:48 offset1:49
	ds_read2_b32 v[6:7], v54 offset0:32 offset1:33
	ds_read2_b32 v[8:9], v54 offset0:50 offset1:51
	ds_read2_b32 v[10:11], v54 offset0:52 offset1:53
	ds_read2_b32 v[12:13], v54 offset0:54 offset1:55
	v_cndmask_b32_e64 v1, v1, 28, s[36:37]
	v_cndmask_b32_e64 v0, v0, 13, s[38:39]
	s_waitcnt lgkmcnt(4)
	v_max_f32_e32 v4, v4, v4
	v_cndmask_b32_e64 v1, v1, 29, s[40:41]
	v_cndmask_b32_e64 v0, v0, 14, s[42:43]
	v_cmp_gt_f32_e64 s[0:1], v15, v3
	v_max_f32_e32 v4, 0xff800000, v4
	s_waitcnt lgkmcnt(3)
	v_max_f32_e32 v6, v6, v6
	v_cndmask_b32_e64 v1, v1, 30, s[44:45]
	v_cndmask_b32_e64 v0, v0, 15, vcc
	v_cndmask_b32_e64 v3, v3, v15, s[0:1]
	ds_read2_b32 v[14:15], v54 offset0:34 offset1:35
	ds_read2_b32 v[16:17], v54 offset0:36 offset1:37
	ds_read2_b32 v[18:19], v54 offset0:38 offset1:39
	v_max_f32_e32 v6, 0xff800000, v6
	v_cmp_gt_f32_e32 vcc, v5, v4
	v_cndmask_b32_e64 v1, v1, 31, s[0:1]
	v_cmp_gt_f32_e64 s[0:1], v7, v6
	v_cndmask_b32_e32 v4, v4, v5, vcc
	s_waitcnt lgkmcnt(5)
	v_cmp_gt_f32_e64 s[8:9], v8, v4
	v_cndmask_b32_e64 v5, v6, v7, s[0:1]
	s_waitcnt lgkmcnt(2)
; DI void peer_topk_item(const Params& p, int tt128, int head, char* smem) {
;     ...
;     for (int g = 0; g < 8; ++g) {
;       float m = -INFINITY; int mi = g * 16;
; #pragma unroll
;       for (int j = 0; j < 16; ++j) { float v = row[g * 16 + j]; if (v > m) { m = v; mi = g * 16 + j; } }
;       gm[g] = m; gi[g] = mi;
;     }
	v_cmp_gt_f32_e64 s[10:11], v14, v5
	v_cndmask_b32_e64 v4, v4, v8, s[8:9]
	v_cmp_gt_f32_e64 s[12:13], v9, v4
	v_cndmask_b32_e64 v5, v5, v14, s[10:11]
	v_cmp_gt_f32_e64 s[14:15], v15, v5
	v_cndmask_b32_e64 v4, v4, v9, s[12:13]
	v_cndmask_b32_e64 v6, 32, 33, s[0:1]
	v_cndmask_b32_e64 v5, v5, v15, s[14:15]
	v_cndmask_b32_e64 v7, 48, 49, vcc
	v_cndmask_b32_e64 v6, v6, 34, s[10:11]
	v_cmp_gt_f32_e32 vcc, v10, v4
	v_cndmask_b32_e64 v6, v6, 35, s[14:15]
	s_waitcnt lgkmcnt(1)
	v_cmp_gt_f32_e64 s[0:1], v16, v5
	v_cndmask_b32_e32 v4, v4, v10, vcc
	v_cndmask_b32_e64 v7, v7, 50, s[8:9]
	v_cndmask_b32_e64 v21, v6, 36, s[0:1]
	v_cndmask_b32_e64 v5, v5, v16, s[0:1]
	v_cmp_gt_f32_e64 s[0:1], v11, v4
	v_cndmask_b32_e64 v7, v7, 51, s[12:13]
	v_cndmask_b32_e64 v20, v7, 52, vcc
	v_cndmask_b32_e64 v15, v4, v11, s[0:1]
	v_cmp_gt_f32_e64 s[10:11], v12, v15
	v_cmp_gt_f32_e32 vcc, v17, v5
	s_nop 0
	v_cndmask_b32_e64 v12, v15, v12, s[10:11]
	v_cndmask_b32_e32 v14, v5, v17, vcc
	v_cmp_gt_f32_e64 s[14:15], v13, v12
	ds_read2_b32 v[4:5], v54 offset0:40 offset1:41
	ds_read2_b32 v[6:7], v54 offset0:42 offset1:43
	ds_read2_b32 v[8:9], v54 offset0:44 offset1:45
	ds_read2_b32 v[10:11], v54 offset0:46 offset1:47
	s_waitcnt lgkmcnt(4)
	v_cmp_gt_f32_e64 s[8:9], v18, v14
	v_cndmask_b32_e64 v22, v12, v13, s[14:15]
	ds_read2_b32 v[12:13], v54 offset0:56 offset1:57
	v_cndmask_b32_e64 v14, v14, v18, s[8:9]
	v_cmp_gt_f32_e64 s[12:13], v19, v14
	s_waitcnt lgkmcnt(0)
	v_cmp_gt_f32_e64 s[18:19], v12, v22
	v_cndmask_b32_e64 v14, v14, v19, s[12:13]
	v_cmp_gt_f32_e64 s[16:17], v4, v14
	v_cndmask_b32_e64 v12, v22, v12, s[18:19]
	v_cmp_gt_f32_e64 s[22:23], v13, v12
	v_cndmask_b32_e64 v4, v14, v4, s[16:17]
	ds_read2_b32 v[14:15], v54 offset0:58 offset1:59
	ds_read2_b32 v[16:17], v54 offset0:60 offset1:61
	ds_read2_b32 v[18:19], v54 offset0:62 offset1:63
	v_cmp_gt_f32_e64 s[20:21], v5, v4
	s_nop 1
	v_cndmask_b32_e64 v4, v4, v5, s[20:21]
	v_cndmask_b32_e64 v5, v12, v13, s[22:23]
	v_cmp_gt_f32_e64 s[24:25], v6, v4
	s_waitcnt lgkmcnt(2)
	v_cmp_gt_f32_e64 s[26:27], v14, v5
	v_cndmask_b32_e64 v4, v4, v6, s[24:25]
	s_nop 0
	v_cndmask_b32_e64 v5, v5, v14, s[26:27]
	v_cmp_gt_f32_e64 s[28:29], v7, v4
	v_cmp_gt_f32_e64 s[30:31], v15, v5
	s_nop 0
	v_cndmask_b32_e64 v4, v4, v7, s[28:29]
	v_cndmask_b32_e64 v5, v5, v15, s[30:31]
	v_cmp_gt_f32_e64 s[34:35], v8, v4
	s_waitcnt lgkmcnt(1)
	v_cmp_gt_f32_e64 s[36:37], v16, v5
	v_cndmask_b32_e64 v4, v4, v8, s[34:35]
	s_nop 0
	v_cndmask_b32_e64 v5, v5, v16, s[36:37]
	v_cmp_gt_f32_e64 s[38:39], v9, v4
	v_cmp_gt_f32_e64 s[40:41], v17, v5
	s_nop 0
	v_cndmask_b32_e64 v4, v4, v9, s[38:39]
	v_cndmask_b32_e64 v5, v5, v17, s[40:41]
	v_cmp_gt_f32_e64 s[42:43], v10, v4
	s_waitcnt lgkmcnt(0)
	v_cmp_gt_f32_e64 s[44:45], v18, v5
	v_cndmask_b32_e64 v6, v4, v10, s[42:43]
	v_cndmask_b32_e64 v4, v21, 37, vcc
	v_cndmask_b32_e64 v7, v5, v18, s[44:45]
	v_cndmask_b32_e64 v5, v20, 53, s[0:1]
	v_cndmask_b32_e64 v4, v4, 38, s[8:9]
	v_cndmask_b32_e64 v5, v5, 54, s[10:11]
	v_cndmask_b32_e64 v4, v4, 39, s[12:13]
	v_cndmask_b32_e64 v5, v5, 55, s[14:15]
	v_cndmask_b32_e64 v4, v4, 40, s[16:17]
	v_cndmask_b32_e64 v5, v5, 56, s[18:19]
	v_cndmask_b32_e64 v4, v4, 41, s[20:21]
	v_cndmask_b32_e64 v5, v5, 57, s[22:23]
	v_cndmask_b32_e64 v4, v4, 42, s[24:25]
	v_cndmask_b32_e64 v5, v5, 58, s[26:27]
	v_cndmask_b32_e64 v4, v4, 43, s[28:29]
	v_cmp_gt_f32_e32 vcc, v11, v6
	v_cndmask_b32_e64 v5, v5, 59, s[30:31]
	v_cndmask_b32_e64 v4, v4, 44, s[34:35]
	v_cndmask_b32_e32 v6, v6, v11, vcc
	ds_read2_b32 v[8:9], v54 offset0:80 offset1:81
	ds_read2_b32 v[10:11], v54 offset0:64 offset1:65
	ds_read2_b32 v[12:13], v54 offset0:82 offset1:83
	ds_read2_b32 v[14:15], v54 offset0:84 offset1:85
	ds_read2_b32 v[16:17], v54 offset0:86 offset1:87
	v_cndmask_b32_e64 v5, v5, 60, s[36:37]
	v_cndmask_b32_e64 v4, v4, 45, s[38:39]
	s_waitcnt lgkmcnt(4)
	v_max_f32_e32 v8, v8, v8
	v_cndmask_b32_e64 v5, v5, 61, s[40:41]
	v_cndmask_b32_e64 v4, v4, 46, s[42:43]
	v_cmp_gt_f32_e64 s[0:1], v19, v7
	v_max_f32_e32 v8, 0xff800000, v8
	s_waitcnt lgkmcnt(3)
	v_max_f32_e32 v10, v10, v10
	v_cndmask_b32_e64 v5, v5, 62, s[44:45]
	v_cndmask_b32_e64 v4, v4, 47, vcc
	v_cndmask_b32_e64 v7, v7, v19, s[0:1]
	ds_read2_b32 v[18:19], v54 offset0:66 offset1:67
	ds_read2_b32 v[20:21], v54 offset0:68 offset1:69
	ds_read2_b32 v[22:23], v54 offset0:70 offset1:71
	v_max_f32_e32 v10, 0xff800000, v10
	v_cmp_gt_f32_e32 vcc, v9, v8
	v_cndmask_b32_e64 v5, v5, 63, s[0:1]
	v_cmp_gt_f32_e64 s[0:1], v11, v10
	v_cndmask_b32_e32 v8, v8, v9, vcc
	s_waitcnt lgkmcnt(5)
	v_cmp_gt_f32_e64 s[8:9], v12, v8
	v_cndmask_b32_e64 v9, v10, v11, s[0:1]
	s_waitcnt lgkmcnt(2)
	v_cmp_gt_f32_e64 s[10:11], v18, v9
	v_cndmask_b32_e64 v8, v8, v12, s[8:9]
	v_cmp_gt_f32_e64 s[12:13], v13, v8
	v_cndmask_b32_e64 v9, v9, v18, s[10:11]
	v_cmp_gt_f32_e64 s[14:15], v19, v9
	v_cndmask_b32_e64 v8, v8, v13, s[12:13]
	v_cndmask_b32_e64 v10, 64, v61, s[0:1]
	v_cndmask_b32_e64 v9, v9, v19, s[14:15]
	v_cndmask_b32_e32 v11, v62, v63, vcc
	v_cndmask_b32_e64 v10, v10, v65, s[10:11]
	v_cmp_gt_f32_e32 vcc, v14, v8
	v_cndmask_b32_e64 v10, v10, v66, s[14:15]
	s_waitcnt lgkmcnt(1)
	v_cmp_gt_f32_e64 s[0:1], v20, v9
	v_cndmask_b32_e32 v8, v8, v14, vcc
	v_cndmask_b32_e64 v11, v11, v64, s[8:9]
	v_cndmask_b32_e64 v25, v10, v69, s[0:1]
	v_cndmask_b32_e64 v9, v9, v20, s[0:1]
	v_cmp_gt_f32_e64 s[0:1], v15, v8
	v_cndmask_b32_e64 v11, v11, v67, s[12:13]
	v_cndmask_b32_e32 v24, v11, v68, vcc
	v_cndmask_b32_e64 v19, v8, v15, s[0:1]
	v_cmp_gt_f32_e64 s[10:11], v16, v19
	v_cmp_gt_f32_e32 vcc, v21, v9
	s_nop 0
	v_cndmask_b32_e64 v16, v19, v16, s[10:11]
	v_cndmask_b32_e32 v18, v9, v21, vcc
	v_cmp_gt_f32_e64 s[14:15], v17, v16
	ds_read2_b32 v[8:9], v54 offset0:72 offset1:73
	ds_read2_b32 v[10:11], v54 offset0:74 offset1:75
	ds_read2_b32 v[12:13], v54 offset0:76 offset1:77
	ds_read2_b32 v[14:15], v54 offset0:78 offset1:79
	s_waitcnt lgkmcnt(4)
; DI void peer_topk_item(const Params& p, int tt128, int head, char* smem) {
;     ...
;     for (int g = 0; g < 8; ++g) {
;       float m = -INFINITY; int mi = g * 16;
; #pragma unroll
;       for (int j = 0; j < 16; ++j) { float v = row[g * 16 + j]; if (v > m) { m = v; mi = g * 16 + j; } }
;       gm[g] = m; gi[g] = mi;
;     }
	v_cmp_gt_f32_e64 s[8:9], v22, v18
	v_cndmask_b32_e64 v26, v16, v17, s[14:15]
	ds_read2_b32 v[16:17], v54 offset0:88 offset1:89
	v_cndmask_b32_e64 v18, v18, v22, s[8:9]
	v_cmp_gt_f32_e64 s[12:13], v23, v18
	s_waitcnt lgkmcnt(0)
	v_cmp_gt_f32_e64 s[18:19], v16, v26
	v_cndmask_b32_e64 v18, v18, v23, s[12:13]
	v_cmp_gt_f32_e64 s[16:17], v8, v18
	v_cndmask_b32_e64 v16, v26, v16, s[18:19]
	v_cmp_gt_f32_e64 s[22:23], v17, v16
	v_cndmask_b32_e64 v8, v18, v8, s[16:17]
	ds_read2_b32 v[18:19], v54 offset0:90 offset1:91
	ds_read2_b32 v[20:21], v54 offset0:92 offset1:93
	ds_read2_b32 v[22:23], v54 offset0:94 offset1:95
	v_cmp_gt_f32_e64 s[20:21], v9, v8
	s_nop 1
	v_cndmask_b32_e64 v8, v8, v9, s[20:21]
	v_cndmask_b32_e64 v9, v16, v17, s[22:23]
	v_cmp_gt_f32_e64 s[24:25], v10, v8
	s_waitcnt lgkmcnt(2)
	v_cmp_gt_f32_e64 s[26:27], v18, v9
	v_cndmask_b32_e64 v8, v8, v10, s[24:25]
	s_nop 0
	v_cndmask_b32_e64 v9, v9, v18, s[26:27]
	v_cmp_gt_f32_e64 s[28:29], v11, v8
	v_cmp_gt_f32_e64 s[30:31], v19, v9
	s_nop 0
	v_cndmask_b32_e64 v8, v8, v11, s[28:29]
	v_cndmask_b32_e64 v9, v9, v19, s[30:31]
	v_cmp_gt_f32_e64 s[34:35], v12, v8
	s_waitcnt lgkmcnt(1)
	v_cmp_gt_f32_e64 s[36:37], v20, v9
	v_cndmask_b32_e64 v8, v8, v12, s[34:35]
	s_nop 0
	v_cndmask_b32_e64 v9, v9, v20, s[36:37]
	v_cmp_gt_f32_e64 s[38:39], v13, v8
	v_cmp_gt_f32_e64 s[40:41], v21, v9
	s_nop 0
	v_cndmask_b32_e64 v8, v8, v13, s[38:39]
	v_cndmask_b32_e64 v9, v9, v21, s[40:41]
	v_cmp_gt_f32_e64 s[42:43], v14, v8
	s_waitcnt lgkmcnt(0)
	v_cmp_gt_f32_e64 s[44:45], v22, v9
	v_cndmask_b32_e64 v10, v8, v14, s[42:43]
	v_cndmask_b32_e32 v8, v25, v70, vcc
	v_cndmask_b32_e64 v11, v9, v22, s[44:45]
	v_cndmask_b32_e64 v9, v24, v71, s[0:1]
	v_cndmask_b32_e64 v8, v8, v73, s[8:9]
	v_cndmask_b32_e64 v9, v9, v72, s[10:11]
	v_cndmask_b32_e64 v8, v8, v74, s[12:13]
	v_cndmask_b32_e64 v9, v9, v75, s[14:15]
	v_cndmask_b32_e64 v8, v8, v77, s[16:17]
	v_cndmask_b32_e64 v9, v9, v76, s[18:19]
	v_cndmask_b32_e64 v8, v8, v78, s[20:21]
	v_cndmask_b32_e64 v9, v9, v79, s[22:23]
	v_cndmask_b32_e64 v8, v8, v81, s[24:25]
	v_cndmask_b32_e64 v9, v9, v80, s[26:27]
	v_cndmask_b32_e64 v8, v8, v82, s[28:29]
	v_cmp_gt_f32_e32 vcc, v15, v10
	v_cndmask_b32_e64 v9, v9, v83, s[30:31]
	v_cndmask_b32_e64 v8, v8, v85, s[34:35]
	v_cndmask_b32_e32 v10, v10, v15, vcc
	ds_read2_b32 v[12:13], v54 offset0:112 offset1:113
	ds_read2_b32 v[14:15], v54 offset0:96 offset1:97
	ds_read2_b32 v[16:17], v54 offset0:114 offset1:115
	ds_read2_b32 v[18:19], v54 offset0:116 offset1:117
	ds_read2_b32 v[20:21], v54 offset0:118 offset1:119
	v_cndmask_b32_e64 v9, v9, v84, s[36:37]
	v_cndmask_b32_e64 v8, v8, v86, s[38:39]
	s_waitcnt lgkmcnt(4)
	v_max_f32_e32 v12, v12, v12
	v_cndmask_b32_e64 v9, v9, v87, s[40:41]
	v_cndmask_b32_e64 v8, v8, v89, s[42:43]
	v_cmp_gt_f32_e64 s[0:1], v23, v11
	v_max_f32_e32 v12, 0xff800000, v12
	s_waitcnt lgkmcnt(3)
	v_max_f32_e32 v14, v14, v14
	v_cndmask_b32_e64 v9, v9, v88, s[44:45]
	v_cndmask_b32_e32 v8, v8, v90, vcc
	v_cndmask_b32_e64 v11, v11, v23, s[0:1]
	ds_read2_b32 v[22:23], v54 offset0:98 offset1:99
	ds_read2_b32 v[24:25], v54 offset0:100 offset1:101
	ds_read2_b32 v[26:27], v54 offset0:102 offset1:103
	v_max_f32_e32 v14, 0xff800000, v14
	v_cmp_gt_f32_e32 vcc, v13, v12
	v_cndmask_b32_e64 v9, v9, v91, s[0:1]
	v_cmp_gt_f32_e64 s[0:1], v15, v14
	v_cndmask_b32_e32 v12, v12, v13, vcc
	s_waitcnt lgkmcnt(5)
	v_cmp_gt_f32_e64 s[8:9], v16, v12
	v_cndmask_b32_e64 v13, v14, v15, s[0:1]
	s_waitcnt lgkmcnt(2)
	v_cmp_gt_f32_e64 s[10:11], v22, v13
	v_cndmask_b32_e64 v12, v12, v16, s[8:9]
	v_cmp_gt_f32_e64 s[12:13], v17, v12
	v_cndmask_b32_e64 v13, v13, v22, s[10:11]
	v_cmp_gt_f32_e64 s[14:15], v23, v13
	v_cndmask_b32_e64 v12, v12, v17, s[12:13]
	v_cndmask_b32_e64 v14, v92, v93, s[0:1]
	v_cndmask_b32_e64 v13, v13, v23, s[14:15]
	v_cndmask_b32_e32 v15, v94, v95, vcc
	v_cndmask_b32_e64 v14, v14, v97, s[10:11]
	v_cmp_gt_f32_e32 vcc, v18, v12
	v_cndmask_b32_e64 v14, v14, v98, s[14:15]
	s_waitcnt lgkmcnt(1)
; DI void peer_topk_item(const Params& p, int tt128, int head, char* smem) {
;     ...
;     for (int g = 0; g < 8; ++g) {
;       float m = -INFINITY; int mi = g * 16;
; #pragma unroll
;       for (int j = 0; j < 16; ++j) { float v = row[g * 16 + j]; if (v > m) { m = v; mi = g * 16 + j; } }
;       gm[g] = m; gi[g] = mi;
;     }
; #pragma unroll 1
	v_cmp_gt_f32_e64 s[0:1], v24, v13
	v_cndmask_b32_e32 v12, v12, v18, vcc
	v_cndmask_b32_e64 v15, v15, v96, s[8:9]
	v_cndmask_b32_e64 v29, v14, v101, s[0:1]
	v_cndmask_b32_e64 v13, v13, v24, s[0:1]
	v_cmp_gt_f32_e64 s[0:1], v19, v12
	v_cndmask_b32_e64 v15, v15, v99, s[12:13]
	v_cndmask_b32_e32 v28, v15, v100, vcc
	v_cndmask_b32_e64 v23, v12, v19, s[0:1]
	v_cmp_gt_f32_e64 s[10:11], v20, v23
	v_cmp_gt_f32_e32 vcc, v25, v13
	s_nop 0
	v_cndmask_b32_e64 v20, v23, v20, s[10:11]
	v_cmp_gt_f32_e64 s[14:15], v21, v20
	v_cndmask_b32_e32 v22, v13, v25, vcc
	ds_read2_b32 v[12:13], v54 offset0:104 offset1:105
	ds_read2_b32 v[14:15], v54 offset0:106 offset1:107
	ds_read2_b32 v[16:17], v54 offset0:108 offset1:109
	ds_read2_b32 v[18:19], v54 offset0:110 offset1:111
	v_cndmask_b32_e64 v30, v20, v21, s[14:15]
	ds_read2_b32 v[20:21], v54 offset0:120 offset1:121
	s_waitcnt lgkmcnt(5)
	v_cmp_gt_f32_e64 s[8:9], v26, v22
	s_waitcnt lgkmcnt(0)
	v_cmp_gt_f32_e64 s[18:19], v20, v30
	v_cndmask_b32_e64 v22, v22, v26, s[8:9]
	v_cmp_gt_f32_e64 s[12:13], v27, v22
	v_cndmask_b32_e64 v20, v30, v20, s[18:19]
	v_cmp_gt_f32_e64 s[22:23], v21, v20
	v_cndmask_b32_e64 v22, v22, v27, s[12:13]
	v_cmp_gt_f32_e64 s[16:17], v12, v22
	s_nop 1
	v_cndmask_b32_e64 v12, v22, v12, s[16:17]
	ds_read2_b32 v[22:23], v54 offset0:122 offset1:123
	ds_read2_b32 v[24:25], v54 offset0:124 offset1:125
	ds_read2_b32 v[26:27], v54 offset0:126 offset1:127
	v_cmp_gt_f32_e64 s[20:21], v13, v12
	s_nop 1
	v_cndmask_b32_e64 v12, v12, v13, s[20:21]
	v_cndmask_b32_e64 v13, v20, v21, s[22:23]
	v_cmp_gt_f32_e64 s[24:25], v14, v12
	s_waitcnt lgkmcnt(2)
	v_cmp_gt_f32_e64 s[26:27], v22, v13
	v_cndmask_b32_e64 v12, v12, v14, s[24:25]
	s_nop 0
	v_cndmask_b32_e64 v13, v13, v22, s[26:27]
	v_cmp_gt_f32_e64 s[28:29], v15, v12
	v_cmp_gt_f32_e64 s[30:31], v23, v13
	s_nop 0
	v_cndmask_b32_e64 v12, v12, v15, s[28:29]
	v_cndmask_b32_e64 v13, v13, v23, s[30:31]
	v_cmp_gt_f32_e64 s[34:35], v16, v12
	s_waitcnt lgkmcnt(1)
	v_cmp_gt_f32_e64 s[36:37], v24, v13
	v_cndmask_b32_e64 v12, v12, v16, s[34:35]
	s_nop 0
	v_cndmask_b32_e64 v13, v13, v24, s[36:37]
	v_cmp_gt_f32_e64 s[38:39], v17, v12
	v_cmp_gt_f32_e64 s[40:41], v25, v13
	v_mov_b32_e32 v16, v55
	v_cndmask_b32_e64 v12, v12, v17, s[38:39]
	v_cndmask_b32_e64 v13, v13, v25, s[40:41]
	v_cmp_gt_f32_e64 s[42:43], v18, v12
	s_waitcnt lgkmcnt(0)
	v_cmp_gt_f32_e64 s[44:45], v26, v13
	v_cndmask_b32_e64 v14, v12, v18, s[42:43]
	s_nop 0
	v_cndmask_b32_e64 v15, v13, v26, s[44:45]
	v_cndmask_b32_e32 v12, v29, v102, vcc
	v_cndmask_b32_e64 v13, v28, v103, s[0:1]
	v_cndmask_b32_e64 v13, v13, v104, s[10:11]
	v_cndmask_b32_e64 v12, v12, v105, s[8:9]
	v_cndmask_b32_e64 v12, v12, v106, s[12:13]
	v_cndmask_b32_e64 v13, v13, v107, s[14:15]
	v_cndmask_b32_e64 v13, v13, v108, s[18:19]
	v_cndmask_b32_e64 v12, v12, v109, s[16:17]
	v_cndmask_b32_e64 v12, v12, v110, s[20:21]
	v_cndmask_b32_e64 v13, v13, v111, s[22:23]
	v_cndmask_b32_e64 v13, v13, v112, s[26:27]
	v_cndmask_b32_e64 v12, v12, v113, s[24:25]
	v_cndmask_b32_e64 v12, v12, v114, s[28:29]
	v_cndmask_b32_e64 v13, v13, v115, s[30:31]
	v_cndmask_b32_e64 v13, v13, v116, s[36:37]
	v_cndmask_b32_e64 v12, v12, v117, s[34:35]
	v_cndmask_b32_e64 v12, v12, v118, s[38:39]
	v_cndmask_b32_e64 v13, v13, v119, s[40:41]
	v_cndmask_b32_e64 v13, v13, v120, s[44:45]
	v_cndmask_b32_e64 v12, v12, v121, s[42:43]
	v_cmp_gt_f32_e32 vcc, v19, v14
	v_cmp_gt_f32_e64 s[0:1], v27, v15
	v_readlane_b32 s20, v255, 5
	v_cndmask_b32_e32 v12, v12, v122, vcc
	v_cndmask_b32_e64 v13, v13, v123, s[0:1]
	v_cndmask_b32_e32 v14, v14, v19, vcc
	v_cndmask_b32_e64 v15, v15, v27, s[0:1]
	v_readlane_b32 s21, v255, 6

; __global__ void __launch_bounds__(512) fwd_megakernel(Params p) {
;   __shared__ __attribute__((aligned(1024))) char smem[155648];
	.amdhsa_kernel _Z14fwd_megakernel6Params
		.amdhsa_group_segment_fixed_size 155648
		.amdhsa_private_segment_fixed_size 0
		.amdhsa_kernarg_size 456
		.amdhsa_user_sgpr_count 2
		.amdhsa_user_sgpr_dispatch_ptr 0
		.amdhsa_user_sgpr_queue_ptr 0
		.amdhsa_user_sgpr_kernarg_segment_ptr 1
		.amdhsa_user_sgpr_dispatch_id 0
		.amdhsa_user_sgpr_kernarg_preload_length 0
		.amdhsa_user_sgpr_kernarg_preload_offset 0
		.amdhsa_user_sgpr_private_segment_size 0
		.amdhsa_uses_dynamic_stack 0
		.amdhsa_enable_private_segment 0
		.amdhsa_system_sgpr_workgroup_id_x 1
		.amdhsa_system_sgpr_workgroup_id_y 0
		.amdhsa_system_sgpr_workgroup_id_z 0
		.amdhsa_system_sgpr_workgroup_info 0
		.amdhsa_system_vgpr_workitem_id 2
		.amdhsa_next_free_vgpr 256
		.amdhsa_next_free_sgpr 102
		.amdhsa_accum_offset 256
		.amdhsa_reserve_vcc 1
		.amdhsa_float_round_mode_32 0
		.amdhsa_float_round_mode_16_64 0
		.amdhsa_float_denorm_mode_32 3
		.amdhsa_float_denorm_mode_16_64 3
		.amdhsa_dx10_clamp 1
		.amdhsa_ieee_mode 1
		.amdhsa_fp16_overflow 0
		.amdhsa_tg_split 0
		.amdhsa_exception_fp_ieee_invalid_op 0
		.amdhsa_exception_fp_denorm_src 0
		.amdhsa_exception_fp_ieee_div_zero 0
		.amdhsa_exception_fp_ieee_overflow 0
		.amdhsa_exception_fp_ieee_underflow 0
		.amdhsa_exception_fp_ieee_inexact 0
		.amdhsa_exception_int_div_zero 0
	.end_amdhsa_kernel

; __global__ void __launch_bounds__(512) fwd_megakernel(Params p) {
;   __shared__ __attribute__((aligned(1024))) char smem[155648];
amdhsa.kernels:
  - .agpr_count:     0
    .args:
      - .offset:         0
        .size:           200
        .value_kind:     by_value
      - .offset:         200
        .size:           4
        .value_kind:     hidden_block_count_x
      - .offset:         204
        .size:           4
        .value_kind:     hidden_block_count_y
      - .offset:         208
        .size:           4
        .value_kind:     hidden_block_count_z
      - .offset:         212
        .size:           2
        .value_kind:     hidden_group_size_x
      - .offset:         214
        .size:           2
        .value_kind:     hidden_group_size_y
      - .offset:         216
        .size:           2
        .value_kind:     hidden_group_size_z
      - .offset:         218
        .size:           2
        .value_kind:     hidden_remainder_x
      - .offset:         220
        .size:           2
        .value_kind:     hidden_remainder_y
      - .offset:         222
        .size:           2
        .value_kind:     hidden_remainder_z
      - .offset:         240
        .size:           8
        .value_kind:     hidden_global_offset_x
      - .offset:         248
        .size:           8
        .value_kind:     hidden_global_offset_y
      - .offset:         256
        .size:           8
        .value_kind:     hidden_global_offset_z
      - .offset:         264
        .size:           2
        .value_kind:     hidden_grid_dims
      - .offset:         288
        .size:           8
        .value_kind:     hidden_multigrid_sync_arg
    .group_segment_fixed_size: 155648
    .kernarg_segment_align: 8
    .kernarg_segment_size: 456
    .language:       OpenCL C
    .language_version:
      - 2
      - 0
    .max_flat_workgroup_size: 512
    .name:           _Z14fwd_megakernel6Params
    .private_segment_fixed_size: 0
    .sgpr_count:     108
    .sgpr_spill_count: 58
    .symbol:         _Z14fwd_megakernel6Params.kd
    .uniform_work_group_size: 1
    .uses_dynamic_stack: false
    .vgpr_count:     256
    .vgpr_spill_count: 0
    .wavefront_size: 64
